# P3 v6: LDS-DMA ring + 3-way wave specialisation (2 o-waves 2x2 tiles, 2 state waves 4x2 tiles, 4 staging waves), 72 ds_read_b128 per step
# speedup vs baseline: 1.0100x; 1.0035x over previous
; #define LAS __attribute__((address_space(3)))
; __device__ __forceinline__ void gla_scan_item(const Ctx& C, int item, LAS unsigned char* lds, int tid) {
;     ...
;     const int wave = tid >> 6, lane = tid & 63, l15 = lane & 15, quad = lane >> 4;
;     f32x4 S[2] = {(f32x4){0.f, 0.f, 0.f, 0.f}, (f32x4){0.f, 0.f, 0.f, 0.f}};
;     *(LAS u32x4*)(Bc + (tid >> 4) * 200 + (tid & 15) * 8) = (u32x4){0u, 0u, 0u, 0u};
;     u32x4 rq0A, rq1A, rsA, rk0A, rk1A, rvA = (u32x4){0u, 0u, 0u, 0u}; f32x4 rdA;
;     u32x4 rq0B, rq1B, rsB, rk0B, rk1B, rvB = (u32x4){0u, 0u, 0u, 0u}; f32x4 rdB;
.LBB0_428:
	s_cmp_lt_i32 s96, 4
	s_cselect_b64 s[4:5], -1, 0
	s_add_u32 s6, s94, 0xb300000
	s_addc_u32 s7, s95, 0
	s_and_b64 s[0:1], s[4:5], s[0:1]
	s_andn2_b64 vcc, exec, s[0:1]
	s_cbranch_vccnz .LBB0_496
	s_cmpk_gt_i32 s2, 0xff
	s_cbranch_scc1 .LBB0_496
	v_readfirstlane_b32 s32, v163
	v_and_b32_e32 v203, 63, v162
	v_and_b32_e32 v202, 15, v162
	v_bfe_u32 v201, v162, 4, 2
	v_lshrrev_b32_e32 v200, 4, v203
	v_lshl_add_u32 v200, v163, 3, v200
	v_and_b32_e32 v199, 15, v200
	v_xor_b32_e32 v199, v199, v202
	v_lshlrev_b32_e32 v255, 10, v200
	v_lshl_add_u32 v255, v199, 4, v255
	v_lshrrev_b32_e32 v200, 4, v203
	v_lshl_add_u32 v200, v163, 3, v200
	v_add_u32_e32 v200, 4, v200
	v_and_b32_e32 v199, 15, v200
	v_xor_b32_e32 v199, v199, v202
	v_lshlrev_b32_e32 v254, 10, v200
	v_lshl_add_u32 v254, v199, 4, v254
	v_lshrrev_b32_e32 v200, 3, v203
	v_lshl_add_u32 v200, v163, 3, v200
	v_bfe_u32 v199, v200, 1, 3
	v_and_b32_e32 v198, 7, v203
	v_xor_b32_e32 v199, v199, v198
	v_lshlrev_b32_e32 v253, 7, v200
	v_lshl_add_u32 v253, v199, 4, v253
	v_lshrrev_b32_e32 v200, 3, v203
	v_lshl_add_u32 v200, v163, 4, v200
	v_bfe_u32 v199, v200, 1, 3
	v_and_b32_e32 v198, 7, v203
	v_xor_b32_e32 v199, v199, v198
	v_lshlrev_b32_e32 v252, 7, v200
	v_lshl_add_u32 v252, v199, 4, v252
	v_lshrrev_b32_e32 v200, 3, v203
	v_lshl_add_u32 v200, v163, 4, v200
	v_add_u32_e32 v200, 8, v200
	v_bfe_u32 v199, v200, 1, 3
	v_and_b32_e32 v198, 7, v203
	v_xor_b32_e32 v199, v199, v198
	v_lshlrev_b32_e32 v251, 7, v200
	v_lshl_add_u32 v251, v199, 4, v251
	s_lshl_b32 s46, s32, 11
	s_lshl_b32 s47, s32, 10
	s_add_i32 s47, s47, 0x4000
	s_add_i32 s48, s46, 0x6000
	v_and_b32_e32 v200, 1, v163
	v_lshl_add_u32 v200, v200, 5, v202
	v_or_b32_e32 v199, 0, v201
	v_and_b32_e32 v198, 15, v200
	v_xor_b32_e32 v199, v199, v198
	v_lshlrev_b32_e32 v241, 8, v200
	v_lshl_add_u32 v241, v199, 4, v241
	v_or_b32_e32 v199, 4, v201
	v_and_b32_e32 v198, 15, v200
	v_xor_b32_e32 v199, v199, v198
	v_lshlrev_b32_e32 v240, 8, v200
	v_lshl_add_u32 v240, v199, 4, v240
	v_or_b32_e32 v199, 8, v201
	v_and_b32_e32 v198, 15, v200
	v_xor_b32_e32 v199, v199, v198
	v_lshlrev_b32_e32 v239, 8, v200
	v_lshl_add_u32 v239, v199, 4, v239
	v_or_b32_e32 v199, 12, v201
	v_and_b32_e32 v198, 15, v200
	v_xor_b32_e32 v199, v199, v198
	v_lshlrev_b32_e32 v238, 8, v200
	v_lshl_add_u32 v238, v199, 4, v238
	v_or_b32_e32 v199, 0, v201
	v_bfe_u32 v198, v200, 1, 3
	v_xor_b32_e32 v199, v199, v198
	v_lshlrev_b32_e32 v231, 7, v200
	v_lshl_add_u32 v231, v199, 4, v231
	v_add_u32_e32 v231, 0x4000, v231
	v_or_b32_e32 v199, 4, v201
	v_bfe_u32 v198, v200, 1, 3
	v_xor_b32_e32 v199, v199, v198
	v_lshlrev_b32_e32 v230, 7, v200
	v_lshl_add_u32 v230, v199, 4, v230
	v_add_u32_e32 v230, 0x4000, v230
	v_lshlrev_b32_e32 v248, 11, v200
	v_lshl_add_u32 v248, v201, 3, v248
	v_add_u32_e32 v247, 0x8000, v248
	v_or_b32_e32 v199, 0, v201
	v_and_b32_e32 v198, 15, v202
	v_xor_b32_e32 v199, v199, v198
	v_lshlrev_b32_e32 v223, 8, v202
	v_lshl_add_u32 v223, v199, 4, v223
	v_add_u32_e32 v223, 0x1e000, v223
	v_or_b32_e32 v199, 4, v201
	v_and_b32_e32 v198, 15, v202
	v_xor_b32_e32 v199, v199, v198
	v_lshlrev_b32_e32 v222, 8, v202
	v_lshl_add_u32 v222, v199, 4, v222
	v_add_u32_e32 v222, 0x1e000, v222
	v_or_b32_e32 v199, 8, v201
	v_and_b32_e32 v198, 15, v202
	v_xor_b32_e32 v199, v199, v198
	v_lshlrev_b32_e32 v221, 8, v202
	v_lshl_add_u32 v221, v199, 4, v221
	v_add_u32_e32 v221, 0x1e000, v221
	v_or_b32_e32 v199, 12, v201
	v_and_b32_e32 v198, 15, v202
	v_xor_b32_e32 v199, v199, v198
	v_lshlrev_b32_e32 v220, 8, v202
	v_lshl_add_u32 v220, v199, 4, v220
	v_add_u32_e32 v220, 0x1e000, v220
	v_or_b32_e32 v199, 0, v201
	v_bfe_u32 v198, v202, 1, 3
	v_xor_b32_e32 v199, v199, v198
	v_lshlrev_b32_e32 v219, 7, v202
	v_lshl_add_u32 v219, v199, 4, v219
	v_add_u32_e32 v219, 0x20100, v219
	v_or_b32_e32 v199, 4, v201
	v_bfe_u32 v198, v202, 1, 3
	v_xor_b32_e32 v199, v199, v198
	v_lshlrev_b32_e32 v218, 7, v202
	v_lshl_add_u32 v218, v199, 4, v218
	v_add_u32_e32 v218, 0x20100, v218
	v_and_b32_e32 v200, 1, v163
	v_lshl_add_u32 v200, v200, 6, v202
	v_or_b32_e32 v199, 0, v201
	v_bfe_u32 v198, v200, 1, 3
	v_xor_b32_e32 v199, v199, v198
	v_lshlrev_b32_e32 v227, 7, v200
	v_lshl_add_u32 v227, v199, 4, v227
	v_add_u32_e32 v227, 0x6000, v227
	v_or_b32_e32 v199, 4, v201
	v_bfe_u32 v198, v200, 1, 3
	v_xor_b32_e32 v199, v199, v198
	v_lshlrev_b32_e32 v226, 7, v200
	v_lshl_add_u32 v226, v199, 4, v226
	v_add_u32_e32 v226, 0x6000, v226
	v_or_b32_e32 v199, 0, v201
	v_bfe_u32 v198, v202, 1, 3
	v_xor_b32_e32 v199, v199, v198
	v_lshlrev_b32_e32 v217, 7, v202
	v_lshl_add_u32 v217, v199, 4, v217
	v_add_u32_e32 v217, 0x20100, v217
	v_or_b32_e32 v199, 4, v201
	v_bfe_u32 v198, v202, 1, 3
	v_xor_b32_e32 v199, v199, v198
	v_lshlrev_b32_e32 v216, 7, v202
; #define LAS __attribute__((address_space(3)))
; __device__ __forceinline__ void gla_scan_item(const Ctx& C, int item, LAS unsigned char* lds, int tid) {
;     ...
;     const int wave = tid >> 6, lane = tid & 63, l15 = lane & 15, quad = lane >> 4;
;     f32x4 S[2] = {(f32x4){0.f, 0.f, 0.f, 0.f}, (f32x4){0.f, 0.f, 0.f, 0.f}};
;     *(LAS u32x4*)(Bc + (tid >> 4) * 200 + (tid & 15) * 8) = (u32x4){0u, 0u, 0u, 0u};
;     u32x4 rq0A, rq1A, rsA, rk0A, rk1A, rvA = (u32x4){0u, 0u, 0u, 0u}; f32x4 rdA;
;     u32x4 rq0B, rq1B, rsB, rk0B, rk1B, rvB = (u32x4){0u, 0u, 0u, 0u}; f32x4 rdB;
;     ...
;     SCAN_LOAD(A, 0); SCAN_LOAD(B, 1);
; #pragma unroll
;     for (int n = 0; n < 32; n += 2) { SCAN_STEP(A, n); SCAN_STEP(B, n + 1); }
;     ...
;     float* So = C.out + OUT_GLAP + ((size_t)bh * 128 + wave * 16 + quad * 4) * 256 + sl * 32 + l15;
; #pragma unroll
;     for (int v2 = 0; v2 < 2; ++v2)
; #pragma unroll
;         for (int j = 0; j < 4; ++j) So[(size_t)j * 256 + v2 * 16] = S[v2][j];
	v_lshl_add_u32 v216, v199, 4, v216
	v_add_u32_e32 v216, 0x20100, v216
	v_add_u32_e32 v235, 0x14000, v241
	v_add_u32_e32 v234, 0x14000, v240
	v_add_u32_e32 v233, 0x14000, v239
	v_add_u32_e32 v232, 0x14000, v238
	v_add_u32_e32 v229, 0x14000, v231
	v_add_u32_e32 v228, 0x14000, v230
	v_add_u32_e32 v225, 0x14000, v227
	v_add_u32_e32 v224, 0x14000, v226
	v_and_b32_e32 v200, 1, v163
	v_lshrrev_b32_e32 v199, 1, v201
	v_lshl_add_u32 v199, v200, 3, v199
	v_xor_b32_e32 v199, v199, v202
	v_lshlrev_b32_e32 v215, 8, v202
	v_lshl_add_u32 v215, v199, 4, v215
	v_and_b32_e32 v199, 1, v201
	v_lshl_add_u32 v215, v199, 3, v215
	v_add_u32_e32 v215, 0x1e000, v215
	v_and_b32_e32 v200, 1, v163
	v_lshrrev_b32_e32 v199, 1, v201
	v_lshl_add_u32 v199, v200, 3, v199
	v_add_u32_e32 v199, 2, v199
	v_xor_b32_e32 v199, v199, v202
	v_lshlrev_b32_e32 v214, 8, v202
	v_lshl_add_u32 v214, v199, 4, v214
	v_and_b32_e32 v199, 1, v201
	v_lshl_add_u32 v214, v199, 3, v214
	v_add_u32_e32 v214, 0x1e000, v214
	v_and_b32_e32 v200, 1, v163
	v_lshrrev_b32_e32 v199, 1, v201
	v_lshl_add_u32 v199, v200, 3, v199
	v_add_u32_e32 v199, 4, v199
	v_xor_b32_e32 v199, v199, v202
	v_lshlrev_b32_e32 v213, 8, v202
	v_lshl_add_u32 v213, v199, 4, v213
	v_and_b32_e32 v199, 1, v201
	v_lshl_add_u32 v213, v199, 3, v213
	v_add_u32_e32 v213, 0x1e000, v213
	v_and_b32_e32 v200, 1, v163
	v_lshrrev_b32_e32 v199, 1, v201
	v_lshl_add_u32 v199, v200, 3, v199
	v_add_u32_e32 v199, 6, v199
	v_xor_b32_e32 v199, v199, v202
	v_lshlrev_b32_e32 v212, 8, v202
	v_lshl_add_u32 v212, v199, 4, v212
	v_and_b32_e32 v199, 1, v201
	v_lshl_add_u32 v212, v199, 3, v212
	v_add_u32_e32 v212, 0x1e000, v212
	v_bfe_u32 v200, v162, 2, 6
	v_and_b32_e32 v198, 3, v162
	v_lshl_add_u32 v199, v198, 3, 0
	v_lshlrev_b32_e32 v211, 7, v199
	v_bfe_u32 v199, v199, 1, 3
	v_lshrrev_b32_e32 v246, 3, v200
	v_xor_b32_e32 v199, v199, v246
	v_lshl_add_u32 v211, v199, 4, v211
	v_and_b32_e32 v199, 7, v200
	v_lshl_add_u32 v211, v199, 1, v211
	v_add_u32_e32 v211, 0x20100, v211
	v_lshl_add_u32 v199, v198, 3, 1
	v_lshlrev_b32_e32 v210, 7, v199
	v_bfe_u32 v199, v199, 1, 3
	v_lshrrev_b32_e32 v246, 3, v200
	v_xor_b32_e32 v199, v199, v246
	v_lshl_add_u32 v210, v199, 4, v210
	v_and_b32_e32 v199, 7, v200
	v_lshl_add_u32 v210, v199, 1, v210
	v_add_u32_e32 v210, 0x20100, v210
	v_lshl_add_u32 v199, v198, 3, 2
	v_lshlrev_b32_e32 v209, 7, v199
	v_bfe_u32 v199, v199, 1, 3
	v_lshrrev_b32_e32 v246, 3, v200
	v_xor_b32_e32 v199, v199, v246
	v_lshl_add_u32 v209, v199, 4, v209
	v_and_b32_e32 v199, 7, v200
	v_lshl_add_u32 v209, v199, 1, v209
	v_add_u32_e32 v209, 0x20100, v209
	v_lshl_add_u32 v199, v198, 3, 3
	v_lshlrev_b32_e32 v208, 7, v199
	v_bfe_u32 v199, v199, 1, 3
	v_lshrrev_b32_e32 v246, 3, v200
	v_xor_b32_e32 v199, v199, v246
	v_lshl_add_u32 v208, v199, 4, v208
	v_and_b32_e32 v199, 7, v200
	v_lshl_add_u32 v208, v199, 1, v208
	v_add_u32_e32 v208, 0x20100, v208
	v_lshl_add_u32 v199, v198, 3, 4
	v_lshlrev_b32_e32 v207, 7, v199
	v_bfe_u32 v199, v199, 1, 3
	v_lshrrev_b32_e32 v246, 3, v200
	v_xor_b32_e32 v199, v199, v246
	v_lshl_add_u32 v207, v199, 4, v207
	v_and_b32_e32 v199, 7, v200
	v_lshl_add_u32 v207, v199, 1, v207
	v_add_u32_e32 v207, 0x20100, v207
	v_lshl_add_u32 v199, v198, 3, 5
	v_lshlrev_b32_e32 v206, 7, v199
	v_bfe_u32 v199, v199, 1, 3
	v_lshrrev_b32_e32 v246, 3, v200
	v_xor_b32_e32 v199, v199, v246
	v_lshl_add_u32 v206, v199, 4, v206
	v_and_b32_e32 v199, 7, v200
	v_lshl_add_u32 v206, v199, 1, v206
	v_add_u32_e32 v206, 0x20100, v206
	v_lshl_add_u32 v199, v198, 3, 6
	v_lshlrev_b32_e32 v205, 7, v199
	v_bfe_u32 v199, v199, 1, 3
	v_lshrrev_b32_e32 v246, 3, v200
	v_xor_b32_e32 v199, v199, v246
	v_lshl_add_u32 v205, v199, 4, v205
	v_and_b32_e32 v199, 7, v200
	v_lshl_add_u32 v205, v199, 1, v205
	v_add_u32_e32 v205, 0x20100, v205
	v_lshl_add_u32 v199, v198, 3, 7
	v_lshlrev_b32_e32 v204, 7, v199
	v_bfe_u32 v199, v199, 1, 3
	v_lshrrev_b32_e32 v246, 3, v200
	v_xor_b32_e32 v199, v199, v246
	v_lshl_add_u32 v204, v199, 4, v204
	v_and_b32_e32 v199, 7, v200
	v_lshl_add_u32 v204, v199, 1, v204
	v_add_u32_e32 v204, 0x20100, v204
	v_bfe_u32 v200, v162, 2, 6
	v_and_b32_e32 v199, 3, v162
	v_lshlrev_b32_e32 v250, 14, v200
	v_lshl_add_u32 v250, v199, 4, v250
	v_and_b32_e32 v200, 1, v163
	v_lshlrev_b32_e32 v249, 8, v200
	v_lshl_add_u32 v249, v201, 4, v249
	v_lshlrev_b32_e32 v245, 16, v200
	v_lshl_add_u32 v245, v201, 12, v245
	v_lshl_add_u32 v245, v202, 2, v245
	v_add_u32_e32 v244, 0x4000, v245
	v_add_u32_e32 v243, 0x8000, v245
	v_add_u32_e32 v242, 0xc000, v245
	v_lshlrev_b32_e32 v246, 4, v162
	v_add_u32_e32 v246, 0x1e000, v246
	v_mov_b32_e32 v8, 0
	v_mov_b32_e32 v9, 0
	v_mov_b32_e32 v10, 0
	v_mov_b32_e32 v11, 0
	s_cmp_gt_u32 s32, 3
	s_cbranch_scc1 .Lp3V_entry
	s_cmp_gt_u32 s32, 1
	s_cbranch_scc1 .Lp3S_entry

; #define LAS __attribute__((address_space(3)))
; __device__ __forceinline__ void gla_scan_item(const Ctx& C, int item, LAS unsigned char* lds, int tid) {
;     const int jx = item >> 3, bh = (item & 7) * 4 + (jx >> 3), sl = jx & 7, b = bh >> 2, h = bh & 3;
;     LAS bf16* Aq = (LAS bf16*)lds;
;     LAS bf16* Bc = (LAS bf16*)(lds + 25600);
;     LAS bf16* Kt = (LAS bf16*)(lds + 38400);
;     const int wave = tid >> 6, lane = tid & 63, l15 = lane & 15, quad = lane >> 4;
;     f32x4 S[2] = {(f32x4){0.f, 0.f, 0.f, 0.f}, (f32x4){0.f, 0.f, 0.f, 0.f}};
;     *(LAS u32x4*)(Bc + (tid >> 4) * 200 + (tid & 15) * 8) = (u32x4){0u, 0u, 0u, 0u};
;     u32x4 rq0A, rq1A, rsA, rk0A, rk1A, rvA = (u32x4){0u, 0u, 0u, 0u}; f32x4 rdA;
;     u32x4 rq0B, rq1B, rsB, rk0B, rk1B, rvB = (u32x4){0u, 0u, 0u, 0u}; f32x4 rdB;
.Lp3O_item:
	s_lshr_b32 s4, s3, 3
	s_and_b32 s41, s4, 7
	s_lshr_b32 s5, s4, 3
	s_and_b32 s37, s3, 7
	s_lshl_b32 s37, s37, 2
	s_add_i32 s37, s37, s5
	s_lshr_b32 s39, s37, 2
	s_and_b32 s40, s37, 3
	s_add_u32 s8, s94, 0x1d800000
	s_addc_u32 s9, s95, 0
	s_lshl_b32 s31, s39, 21
	s_add_u32 s8, s8, s31
	s_addc_u32 s9, s9, 0
	s_lshl_b32 s31, s40, 8
	s_add_u32 s8, s8, s31
	s_addc_u32 s9, s9, 0
	s_add_u32 s10, s94, 0x2f00000
	s_addc_u32 s11, s95, 0
	s_lshl_b32 s31, s37, 18
	s_add_u32 s10, s10, s31
	s_addc_u32 s11, s11, 0
	s_add_u32 s12, s94, 0x3700000
	s_addc_u32 s13, s95, 0
	s_lshl_b32 s31, s37, 19
	s_add_u32 s12, s12, s31
	s_addc_u32 s13, s13, 0
	s_add_u32 s18, s6, 0x0
	s_addc_u32 s19, s7, 0
	s_lshl_b32 s31, s39, 22
	s_add_u32 s18, s18, s31
	s_addc_u32 s19, s19, 0
	s_lshl_b32 s31, s40, 9
	s_add_u32 s18, s18, s31
	s_addc_u32 s19, s19, 0
	s_lshl_b32 s31, s41, 6
	s_add_u32 s18, s18, s31
	s_addc_u32 s19, s19, 0
	ds_write_b128 v246, v[8:11]
	s_mov_b32 m0, s46
	s_nop 0
	global_load_lds_dwordx4 v255, s[8:9]
	s_add_i32 m0, s46, 0x400
	s_nop 0
	global_load_lds_dwordx4 v254, s[8:9]
	s_mov_b32 m0, s47
	s_nop 0
	global_load_lds_dwordx4 v253, s[10:11]
	s_mov_b32 m0, s48
	s_nop 0
	global_load_lds_dwordx4 v252, s[12:13]
	s_add_i32 m0, s48, 0x400
	s_nop 0
	global_load_lds_dwordx4 v251, s[12:13]
	s_add_u32 s8, s8, 0x10000
	s_addc_u32 s9, s9, 0
	s_add_u32 s10, s10, 0x2000
	s_addc_u32 s11, s11, 0
	s_add_u32 s12, s12, 0x4000
	s_addc_u32 s13, s13, 0
	s_add_i32 m0, s46, 0xa000
	s_nop 0
	global_load_lds_dwordx4 v255, s[8:9]
	s_add_i32 m0, s46, 0xa400
	s_nop 0
	global_load_lds_dwordx4 v254, s[8:9]
	s_add_i32 m0, s47, 0xa000
	s_nop 0
	global_load_lds_dwordx4 v253, s[10:11]
	s_add_i32 m0, s48, 0xa000
	s_nop 0
	global_load_lds_dwordx4 v252, s[12:13]
	s_add_i32 m0, s48, 0xa400
	s_nop 0
	global_load_lds_dwordx4 v251, s[12:13]
	s_add_u32 s8, s8, 0x10000
	s_addc_u32 s9, s9, 0
	s_add_u32 s10, s10, 0x2000
	s_addc_u32 s11, s11, 0
	s_add_u32 s12, s12, 0x4000
	s_addc_u32 s13, s13, 0
	s_waitcnt vmcnt(0)
	s_mov_b32 s33, 0
	s_waitcnt lgkmcnt(0)
	s_barrier
.Lp3O_loop:
	ds_read_b128 v[60:63], v241 offset:0
	ds_read_b128 v[12:15], v223 offset:0
	ds_read_b128 v[16:19], v223 offset:4096
	ds_read_b128 v[64:67], v241 offset:4096
	ds_read_b128 v[68:71], v240 offset:0
	ds_read_b128 v[20:23], v222 offset:0
	ds_read_b128 v[24:27], v222 offset:4096
	ds_read_b128 v[72:75], v240 offset:4096
	ds_read_b128 v[76:79], v239 offset:0
	ds_read_b128 v[28:31], v221 offset:0
	ds_read_b128 v[32:35], v221 offset:4096
	ds_read_b128 v[80:83], v239 offset:4096
	s_add_i32 m0, s46, 0x14000
	s_nop 0
	global_load_lds_dwordx4 v255, s[8:9]
	s_add_i32 m0, s46, 0x14400
	s_nop 0
	global_load_lds_dwordx4 v254, s[8:9]
	s_add_i32 m0, s47, 0x14000
	s_nop 0
	global_load_lds_dwordx4 v253, s[10:11]
	s_add_i32 m0, s48, 0x14000
	s_nop 0
	global_load_lds_dwordx4 v252, s[12:13]
	s_add_i32 m0, s48, 0x14400
	s_nop 0
	global_load_lds_dwordx4 v251, s[12:13]
	s_cmp_lt_u32 s33, 29
	s_cselect_b32 s43, 0x10000, 0
	s_add_u32 s8, s8, s43
	s_addc_u32 s9, s9, 0
	s_cmp_lt_u32 s33, 29
	s_cselect_b32 s43, 0x2000, 0
	s_add_u32 s10, s10, s43
	s_addc_u32 s11, s11, 0
	s_cmp_lt_u32 s33, 29
	s_cselect_b32 s43, 0x4000, 0
	s_add_u32 s12, s12, s43
	s_addc_u32 s13, s13, 0
	s_waitcnt lgkmcnt(8)
	v_mfma_f32_16x16x32_bf16 v[108:111], v[12:15], v[60:63], 0
	v_mfma_f32_16x16x32_bf16 v[112:115], v[16:19], v[60:63], 0
	v_mfma_f32_16x16x32_bf16 v[116:119], v[12:15], v[64:67], 0
	v_mfma_f32_16x16x32_bf16 v[120:123], v[16:19], v[64:67], 0
	ds_read_b128 v[84:87], v238 offset:0
	ds_read_b128 v[36:39], v220 offset:0
	ds_read_b128 v[40:43], v220 offset:4096
	ds_read_b128 v[88:91], v238 offset:4096
	s_waitcnt lgkmcnt(8)
	v_mfma_f32_16x16x32_bf16 v[108:111], v[20:23], v[68:71], v[108:111]
	v_mfma_f32_16x16x32_bf16 v[112:115], v[24:27], v[68:71], v[112:115]
	v_mfma_f32_16x16x32_bf16 v[116:119], v[20:23], v[72:75], v[116:119]
	v_mfma_f32_16x16x32_bf16 v[120:123], v[24:27], v[72:75], v[120:123]
	ds_read_b128 v[92:95], v231 offset:0
	ds_read_b128 v[44:47], v219 offset:0
	ds_read_b128 v[48:51], v219 offset:2048
	ds_read_b128 v[96:99], v231 offset:2048
	s_waitcnt lgkmcnt(8)
	v_mfma_f32_16x16x32_bf16 v[108:111], v[28:31], v[76:79], v[108:111]
	v_mfma_f32_16x16x32_bf16 v[112:115], v[32:35], v[76:79], v[112:115]
	v_mfma_f32_16x16x32_bf16 v[116:119], v[28:31], v[80:83], v[116:119]
	v_mfma_f32_16x16x32_bf16 v[120:123], v[32:35], v[80:83], v[120:123]
	ds_read_b128 v[100:103], v230 offset:0
	ds_read_b128 v[52:55], v218 offset:0
	ds_read_b128 v[56:59], v218 offset:2048
	ds_read_b128 v[104:107], v230 offset:2048
	s_waitcnt lgkmcnt(8)
	v_mfma_f32_16x16x32_bf16 v[108:111], v[36:39], v[84:87], v[108:111]
	v_mfma_f32_16x16x32_bf16 v[112:115], v[40:43], v[84:87], v[112:115]
	v_mfma_f32_16x16x32_bf16 v[116:119], v[36:39], v[88:91], v[116:119]
	v_mfma_f32_16x16x32_bf16 v[120:123], v[40:43], v[88:91], v[120:123]
	s_waitcnt lgkmcnt(4)
	v_mfma_f32_16x16x32_bf16 v[108:111], v[44:47], v[92:95], v[108:111]
	v_mfma_f32_16x16x32_bf16 v[112:115], v[48:51], v[92:95], v[112:115]
	v_mfma_f32_16x16x32_bf16 v[116:119], v[44:47], v[96:99], v[116:119]
	v_mfma_f32_16x16x32_bf16 v[120:123], v[48:51], v[96:99], v[120:123]
	s_waitcnt lgkmcnt(0)
	v_mfma_f32_16x16x32_bf16 v[108:111], v[52:55], v[100:103], v[108:111]
	v_mfma_f32_16x16x32_bf16 v[112:115], v[56:59], v[100:103], v[112:115]
	v_mfma_f32_16x16x32_bf16 v[116:119], v[52:55], v[104:107], v[116:119]
	v_mfma_f32_16x16x32_bf16 v[120:123], v[56:59], v[104:107], v[120:123]
	s_nop 7
	s_nop 7
	v_cvt_pk_bf16_f32 v124, v108, v109
	v_cvt_pk_bf16_f32 v125, v110, v111
	v_cvt_pk_bf16_f32 v126, v112, v113
	v_cvt_pk_bf16_f32 v127, v114, v115
	v_cvt_pk_bf16_f32 v128, v116, v117
	v_cvt_pk_bf16_f32 v129, v118, v119
	v_cvt_pk_bf16_f32 v130, v120, v121
	v_cvt_pk_bf16_f32 v131, v122, v123
	global_store_dwordx2 v248, v[124:125], s[18:19]
	global_store_dwordx2 v248, v[126:127], s[18:19] offset:32
	global_store_dwordx2 v247, v[128:129], s[18:19]
	global_store_dwordx2 v247, v[130:131], s[18:19] offset:32
	s_add_u32 s18, s18, 0x20000
	s_addc_u32 s19, s19, 0
	s_add_i32 s33, s33, 1
	s_waitcnt vmcnt(13)
	s_waitcnt lgkmcnt(0)
	s_barrier
	ds_read_b128 v[60:63], v241 offset:40960
	ds_read_b128 v[12:15], v223 offset:12544
	ds_read_b128 v[16:19], v223 offset:16640
	ds_read_b128 v[64:67], v241 offset:45056
	ds_read_b128 v[68:71], v240 offset:40960
	ds_read_b128 v[20:23], v222 offset:12544
	ds_read_b128 v[24:27], v222 offset:16640
	ds_read_b128 v[72:75], v240 offset:45056
	ds_read_b128 v[76:79], v239 offset:40960
	ds_read_b128 v[28:31], v221 offset:12544
	ds_read_b128 v[32:35], v221 offset:16640
	ds_read_b128 v[80:83], v239 offset:45056
	s_mov_b32 m0, s46
	s_nop 0
	global_load_lds_dwordx4 v255, s[8:9]
	s_add_i32 m0, s46, 0x400
	s_nop 0
	global_load_lds_dwordx4 v254, s[8:9]
	s_mov_b32 m0, s47
	s_nop 0
	global_load_lds_dwordx4 v253, s[10:11]
	s_mov_b32 m0, s48
	s_nop 0
	global_load_lds_dwordx4 v252, s[12:13]
	s_add_i32 m0, s48, 0x400
	s_nop 0
	global_load_lds_dwordx4 v251, s[12:13]
	s_cmp_lt_u32 s33, 29
	s_cselect_b32 s43, 0x10000, 0
	s_add_u32 s8, s8, s43
	s_addc_u32 s9, s9, 0
	s_cmp_lt_u32 s33, 29
	s_cselect_b32 s43, 0x2000, 0
	s_add_u32 s10, s10, s43
	s_addc_u32 s11, s11, 0
	s_cmp_lt_u32 s33, 29
	s_cselect_b32 s43, 0x4000, 0
	s_add_u32 s12, s12, s43
	s_addc_u32 s13, s13, 0
	s_waitcnt lgkmcnt(8)
	v_mfma_f32_16x16x32_bf16 v[108:111], v[12:15], v[60:63], 0
	v_mfma_f32_16x16x32_bf16 v[112:115], v[16:19], v[60:63], 0
	v_mfma_f32_16x16x32_bf16 v[116:119], v[12:15], v[64:67], 0
	v_mfma_f32_16x16x32_bf16 v[120:123], v[16:19], v[64:67], 0
	ds_read_b128 v[84:87], v238 offset:40960
	ds_read_b128 v[36:39], v220 offset:12544
	ds_read_b128 v[40:43], v220 offset:16640
	ds_read_b128 v[88:91], v238 offset:45056
	s_waitcnt lgkmcnt(8)
	v_mfma_f32_16x16x32_bf16 v[108:111], v[20:23], v[68:71], v[108:111]
	v_mfma_f32_16x16x32_bf16 v[112:115], v[24:27], v[68:71], v[112:115]
	v_mfma_f32_16x16x32_bf16 v[116:119], v[20:23], v[72:75], v[116:119]
	v_mfma_f32_16x16x32_bf16 v[120:123], v[24:27], v[72:75], v[120:123]
	ds_read_b128 v[92:95], v231 offset:40960
	ds_read_b128 v[44:47], v219 offset:12288
	ds_read_b128 v[48:51], v219 offset:14336
	ds_read_b128 v[96:99], v231 offset:43008
	s_waitcnt lgkmcnt(8)
	v_mfma_f32_16x16x32_bf16 v[108:111], v[28:31], v[76:79], v[108:111]
	v_mfma_f32_16x16x32_bf16 v[112:115], v[32:35], v[76:79], v[112:115]
	v_mfma_f32_16x16x32_bf16 v[116:119], v[28:31], v[80:83], v[116:119]
	v_mfma_f32_16x16x32_bf16 v[120:123], v[32:35], v[80:83], v[120:123]
	ds_read_b128 v[100:103], v230 offset:40960
	ds_read_b128 v[52:55], v218 offset:12288
	ds_read_b128 v[56:59], v218 offset:14336
	ds_read_b128 v[104:107], v230 offset:43008
	s_waitcnt lgkmcnt(8)
	v_mfma_f32_16x16x32_bf16 v[108:111], v[36:39], v[84:87], v[108:111]
	v_mfma_f32_16x16x32_bf16 v[112:115], v[40:43], v[84:87], v[112:115]
	v_mfma_f32_16x16x32_bf16 v[116:119], v[36:39], v[88:91], v[116:119]
	v_mfma_f32_16x16x32_bf16 v[120:123], v[40:43], v[88:91], v[120:123]
	s_waitcnt lgkmcnt(4)
	v_mfma_f32_16x16x32_bf16 v[108:111], v[44:47], v[92:95], v[108:111]
	v_mfma_f32_16x16x32_bf16 v[112:115], v[48:51], v[92:95], v[112:115]
	v_mfma_f32_16x16x32_bf16 v[116:119], v[44:47], v[96:99], v[116:119]
	v_mfma_f32_16x16x32_bf16 v[120:123], v[48:51], v[96:99], v[120:123]
	s_waitcnt lgkmcnt(0)
	v_mfma_f32_16x16x32_bf16 v[108:111], v[52:55], v[100:103], v[108:111]
	v_mfma_f32_16x16x32_bf16 v[112:115], v[56:59], v[100:103], v[112:115]
	v_mfma_f32_16x16x32_bf16 v[116:119], v[52:55], v[104:107], v[116:119]
	v_mfma_f32_16x16x32_bf16 v[120:123], v[56:59], v[104:107], v[120:123]
	s_nop 7
	s_nop 7
	v_cvt_pk_bf16_f32 v124, v108, v109
	v_cvt_pk_bf16_f32 v125, v110, v111
	v_cvt_pk_bf16_f32 v126, v112, v113
	v_cvt_pk_bf16_f32 v127, v114, v115
	v_cvt_pk_bf16_f32 v128, v116, v117
	v_cvt_pk_bf16_f32 v129, v118, v119
	v_cvt_pk_bf16_f32 v130, v120, v121
	v_cvt_pk_bf16_f32 v131, v122, v123
	global_store_dwordx2 v248, v[124:125], s[18:19]
	global_store_dwordx2 v248, v[126:127], s[18:19] offset:32
	global_store_dwordx2 v247, v[128:129], s[18:19]
	global_store_dwordx2 v247, v[130:131], s[18:19] offset:32
	s_add_u32 s18, s18, 0x20000
	s_addc_u32 s19, s19, 0
	s_add_i32 s33, s33, 1
	s_waitcnt vmcnt(13)
	s_waitcnt lgkmcnt(0)
	s_barrier
	ds_read_b128 v[60:63], v235 offset:0
	ds_read_b128 v[12:15], v223 offset:0
	ds_read_b128 v[16:19], v223 offset:4096
	ds_read_b128 v[64:67], v235 offset:4096
	ds_read_b128 v[68:71], v234 offset:0
	ds_read_b128 v[20:23], v222 offset:0
	ds_read_b128 v[24:27], v222 offset:4096
	ds_read_b128 v[72:75], v234 offset:4096
	ds_read_b128 v[76:79], v233 offset:0
	ds_read_b128 v[28:31], v221 offset:0
	ds_read_b128 v[32:35], v221 offset:4096
	ds_read_b128 v[80:83], v233 offset:4096
	s_add_i32 m0, s46, 0xa000
	s_nop 0
	global_load_lds_dwordx4 v255, s[8:9]
	s_add_i32 m0, s46, 0xa400
	s_nop 0
	global_load_lds_dwordx4 v254, s[8:9]
	s_add_i32 m0, s47, 0xa000
	s_nop 0
	global_load_lds_dwordx4 v253, s[10:11]
	s_add_i32 m0, s48, 0xa000
	s_nop 0
	global_load_lds_dwordx4 v252, s[12:13]
	s_add_i32 m0, s48, 0xa400
	s_nop 0
	global_load_lds_dwordx4 v251, s[12:13]
	s_cmp_lt_u32 s33, 29
	s_cselect_b32 s43, 0x10000, 0
	s_add_u32 s8, s8, s43
	s_addc_u32 s9, s9, 0
	s_cmp_lt_u32 s33, 29
	s_cselect_b32 s43, 0x2000, 0
	s_add_u32 s10, s10, s43
	s_addc_u32 s11, s11, 0
	s_cmp_lt_u32 s33, 29
	s_cselect_b32 s43, 0x4000, 0
	s_add_u32 s12, s12, s43
	s_addc_u32 s13, s13, 0
	s_waitcnt lgkmcnt(8)
	v_mfma_f32_16x16x32_bf16 v[108:111], v[12:15], v[60:63], 0
	v_mfma_f32_16x16x32_bf16 v[112:115], v[16:19], v[60:63], 0
	v_mfma_f32_16x16x32_bf16 v[116:119], v[12:15], v[64:67], 0
	v_mfma_f32_16x16x32_bf16 v[120:123], v[16:19], v[64:67], 0
	ds_read_b128 v[84:87], v232 offset:0
	ds_read_b128 v[36:39], v220 offset:0
	ds_read_b128 v[40:43], v220 offset:4096
	ds_read_b128 v[88:91], v232 offset:4096
	s_waitcnt lgkmcnt(8)
	v_mfma_f32_16x16x32_bf16 v[108:111], v[20:23], v[68:71], v[108:111]
	v_mfma_f32_16x16x32_bf16 v[112:115], v[24:27], v[68:71], v[112:115]
	v_mfma_f32_16x16x32_bf16 v[116:119], v[20:23], v[72:75], v[116:119]
	v_mfma_f32_16x16x32_bf16 v[120:123], v[24:27], v[72:75], v[120:123]
	ds_read_b128 v[92:95], v229 offset:0
	ds_read_b128 v[44:47], v219 offset:0
	ds_read_b128 v[48:51], v219 offset:2048
	ds_read_b128 v[96:99], v229 offset:2048
	s_waitcnt lgkmcnt(8)
	v_mfma_f32_16x16x32_bf16 v[108:111], v[28:31], v[76:79], v[108:111]
	v_mfma_f32_16x16x32_bf16 v[112:115], v[32:35], v[76:79], v[112:115]
	v_mfma_f32_16x16x32_bf16 v[116:119], v[28:31], v[80:83], v[116:119]
	v_mfma_f32_16x16x32_bf16 v[120:123], v[32:35], v[80:83], v[120:123]
	ds_read_b128 v[100:103], v228 offset:0
	ds_read_b128 v[52:55], v218 offset:0
	ds_read_b128 v[56:59], v218 offset:2048
	ds_read_b128 v[104:107], v228 offset:2048
	s_waitcnt lgkmcnt(8)
	v_mfma_f32_16x16x32_bf16 v[108:111], v[36:39], v[84:87], v[108:111]
	v_mfma_f32_16x16x32_bf16 v[112:115], v[40:43], v[84:87], v[112:115]
	v_mfma_f32_16x16x32_bf16 v[116:119], v[36:39], v[88:91], v[116:119]
	v_mfma_f32_16x16x32_bf16 v[120:123], v[40:43], v[88:91], v[120:123]
	s_waitcnt lgkmcnt(4)
	v_mfma_f32_16x16x32_bf16 v[108:111], v[44:47], v[92:95], v[108:111]
	v_mfma_f32_16x16x32_bf16 v[112:115], v[48:51], v[92:95], v[112:115]
	v_mfma_f32_16x16x32_bf16 v[116:119], v[44:47], v[96:99], v[116:119]
	v_mfma_f32_16x16x32_bf16 v[120:123], v[48:51], v[96:99], v[120:123]
	s_waitcnt lgkmcnt(0)
	v_mfma_f32_16x16x32_bf16 v[108:111], v[52:55], v[100:103], v[108:111]
	v_mfma_f32_16x16x32_bf16 v[112:115], v[56:59], v[100:103], v[112:115]
	v_mfma_f32_16x16x32_bf16 v[116:119], v[52:55], v[104:107], v[116:119]
	v_mfma_f32_16x16x32_bf16 v[120:123], v[56:59], v[104:107], v[120:123]
	s_nop 7
	s_nop 7
	v_cvt_pk_bf16_f32 v124, v108, v109
	v_cvt_pk_bf16_f32 v125, v110, v111
	v_cvt_pk_bf16_f32 v126, v112, v113
	v_cvt_pk_bf16_f32 v127, v114, v115
	v_cvt_pk_bf16_f32 v128, v116, v117
	v_cvt_pk_bf16_f32 v129, v118, v119
	v_cvt_pk_bf16_f32 v130, v120, v121
	v_cvt_pk_bf16_f32 v131, v122, v123
	global_store_dwordx2 v248, v[124:125], s[18:19]
	global_store_dwordx2 v248, v[126:127], s[18:19] offset:32
	global_store_dwordx2 v247, v[128:129], s[18:19]
	global_store_dwordx2 v247, v[130:131], s[18:19] offset:32
	s_add_u32 s18, s18, 0x20000
	s_addc_u32 s19, s19, 0
	s_add_i32 s33, s33, 1
	s_waitcnt vmcnt(13)
	s_waitcnt lgkmcnt(0)
	s_barrier
	ds_read_b128 v[60:63], v241 offset:0
	ds_read_b128 v[12:15], v223 offset:12544
	ds_read_b128 v[16:19], v223 offset:16640
	ds_read_b128 v[64:67], v241 offset:4096
	ds_read_b128 v[68:71], v240 offset:0
	ds_read_b128 v[20:23], v222 offset:12544
	ds_read_b128 v[24:27], v222 offset:16640
	ds_read_b128 v[72:75], v240 offset:4096
	ds_read_b128 v[76:79], v239 offset:0
	ds_read_b128 v[28:31], v221 offset:12544
	ds_read_b128 v[32:35], v221 offset:16640
	ds_read_b128 v[80:83], v239 offset:4096
	s_add_i32 m0, s46, 0x14000
	s_nop 0
	global_load_lds_dwordx4 v255, s[8:9]
	s_add_i32 m0, s46, 0x14400
	s_nop 0
	global_load_lds_dwordx4 v254, s[8:9]
	s_add_i32 m0, s47, 0x14000
	s_nop 0
	global_load_lds_dwordx4 v253, s[10:11]
	s_add_i32 m0, s48, 0x14000
	s_nop 0
	global_load_lds_dwordx4 v252, s[12:13]
	s_add_i32 m0, s48, 0x14400
	s_nop 0
	global_load_lds_dwordx4 v251, s[12:13]
	s_cmp_lt_u32 s33, 29
	s_cselect_b32 s43, 0x10000, 0
	s_add_u32 s8, s8, s43
	s_addc_u32 s9, s9, 0
	s_cmp_lt_u32 s33, 29
	s_cselect_b32 s43, 0x2000, 0
	s_add_u32 s10, s10, s43
	s_addc_u32 s11, s11, 0
	s_cmp_lt_u32 s33, 29
	s_cselect_b32 s43, 0x4000, 0
	s_add_u32 s12, s12, s43
	s_addc_u32 s13, s13, 0
	s_waitcnt lgkmcnt(8)
	v_mfma_f32_16x16x32_bf16 v[108:111], v[12:15], v[60:63], 0
	v_mfma_f32_16x16x32_bf16 v[112:115], v[16:19], v[60:63], 0
	v_mfma_f32_16x16x32_bf16 v[116:119], v[12:15], v[64:67], 0
	v_mfma_f32_16x16x32_bf16 v[120:123], v[16:19], v[64:67], 0
	ds_read_b128 v[84:87], v238 offset:0
	ds_read_b128 v[36:39], v220 offset:12544
	ds_read_b128 v[40:43], v220 offset:16640
	ds_read_b128 v[88:91], v238 offset:4096
	s_waitcnt lgkmcnt(8)
	v_mfma_f32_16x16x32_bf16 v[108:111], v[20:23], v[68:71], v[108:111]
	v_mfma_f32_16x16x32_bf16 v[112:115], v[24:27], v[68:71], v[112:115]
	v_mfma_f32_16x16x32_bf16 v[116:119], v[20:23], v[72:75], v[116:119]
	v_mfma_f32_16x16x32_bf16 v[120:123], v[24:27], v[72:75], v[120:123]
	ds_read_b128 v[92:95], v231 offset:0
	ds_read_b128 v[44:47], v219 offset:12288
	ds_read_b128 v[48:51], v219 offset:14336
	ds_read_b128 v[96:99], v231 offset:2048
	s_waitcnt lgkmcnt(8)
	v_mfma_f32_16x16x32_bf16 v[108:111], v[28:31], v[76:79], v[108:111]
	v_mfma_f32_16x16x32_bf16 v[112:115], v[32:35], v[76:79], v[112:115]
	v_mfma_f32_16x16x32_bf16 v[116:119], v[28:31], v[80:83], v[116:119]
	v_mfma_f32_16x16x32_bf16 v[120:123], v[32:35], v[80:83], v[120:123]
	ds_read_b128 v[100:103], v230 offset:0
	ds_read_b128 v[52:55], v218 offset:12288
	ds_read_b128 v[56:59], v218 offset:14336
	ds_read_b128 v[104:107], v230 offset:2048
	s_waitcnt lgkmcnt(8)
	v_mfma_f32_16x16x32_bf16 v[108:111], v[36:39], v[84:87], v[108:111]
	v_mfma_f32_16x16x32_bf16 v[112:115], v[40:43], v[84:87], v[112:115]
	v_mfma_f32_16x16x32_bf16 v[116:119], v[36:39], v[88:91], v[116:119]
	v_mfma_f32_16x16x32_bf16 v[120:123], v[40:43], v[88:91], v[120:123]
	s_waitcnt lgkmcnt(4)
	v_mfma_f32_16x16x32_bf16 v[108:111], v[44:47], v[92:95], v[108:111]
	v_mfma_f32_16x16x32_bf16 v[112:115], v[48:51], v[92:95], v[112:115]
	v_mfma_f32_16x16x32_bf16 v[116:119], v[44:47], v[96:99], v[116:119]
	v_mfma_f32_16x16x32_bf16 v[120:123], v[48:51], v[96:99], v[120:123]
	s_waitcnt lgkmcnt(0)
	v_mfma_f32_16x16x32_bf16 v[108:111], v[52:55], v[100:103], v[108:111]
	v_mfma_f32_16x16x32_bf16 v[112:115], v[56:59], v[100:103], v[112:115]
	v_mfma_f32_16x16x32_bf16 v[116:119], v[52:55], v[104:107], v[116:119]
	v_mfma_f32_16x16x32_bf16 v[120:123], v[56:59], v[104:107], v[120:123]
	s_nop 7
	s_nop 7
	v_cvt_pk_bf16_f32 v124, v108, v109
	v_cvt_pk_bf16_f32 v125, v110, v111
	v_cvt_pk_bf16_f32 v126, v112, v113
	v_cvt_pk_bf16_f32 v127, v114, v115
	v_cvt_pk_bf16_f32 v128, v116, v117
	v_cvt_pk_bf16_f32 v129, v118, v119
	v_cvt_pk_bf16_f32 v130, v120, v121
	v_cvt_pk_bf16_f32 v131, v122, v123
	global_store_dwordx2 v248, v[124:125], s[18:19]
	global_store_dwordx2 v248, v[126:127], s[18:19] offset:32
	global_store_dwordx2 v247, v[128:129], s[18:19]
	global_store_dwordx2 v247, v[130:131], s[18:19] offset:32
	s_add_u32 s18, s18, 0x20000
	s_addc_u32 s19, s19, 0
	s_add_i32 s33, s33, 1
	s_waitcnt vmcnt(13)
	s_waitcnt lgkmcnt(0)
	s_barrier
	ds_read_b128 v[60:63], v241 offset:40960
	ds_read_b128 v[12:15], v223 offset:0
	ds_read_b128 v[16:19], v223 offset:4096
	ds_read_b128 v[64:67], v241 offset:45056
	ds_read_b128 v[68:71], v240 offset:40960
	ds_read_b128 v[20:23], v222 offset:0
	ds_read_b128 v[24:27], v222 offset:4096
	ds_read_b128 v[72:75], v240 offset:45056
	ds_read_b128 v[76:79], v239 offset:40960
	ds_read_b128 v[28:31], v221 offset:0
	ds_read_b128 v[32:35], v221 offset:4096
	ds_read_b128 v[80:83], v239 offset:45056
	s_mov_b32 m0, s46
	s_nop 0
	global_load_lds_dwordx4 v255, s[8:9]
	s_add_i32 m0, s46, 0x400
	s_nop 0
	global_load_lds_dwordx4 v254, s[8:9]
	s_mov_b32 m0, s47
	s_nop 0
	global_load_lds_dwordx4 v253, s[10:11]
	s_mov_b32 m0, s48
	s_nop 0
	global_load_lds_dwordx4 v252, s[12:13]
	s_add_i32 m0, s48, 0x400
	s_nop 0
	global_load_lds_dwordx4 v251, s[12:13]
	s_cmp_lt_u32 s33, 29
	s_cselect_b32 s43, 0x10000, 0
	s_add_u32 s8, s8, s43
	s_addc_u32 s9, s9, 0
	s_cmp_lt_u32 s33, 29
	s_cselect_b32 s43, 0x2000, 0
	s_add_u32 s10, s10, s43
	s_addc_u32 s11, s11, 0
	s_cmp_lt_u32 s33, 29
	s_cselect_b32 s43, 0x4000, 0
	s_add_u32 s12, s12, s43
	s_addc_u32 s13, s13, 0
	s_waitcnt lgkmcnt(8)
	v_mfma_f32_16x16x32_bf16 v[108:111], v[12:15], v[60:63], 0
	v_mfma_f32_16x16x32_bf16 v[112:115], v[16:19], v[60:63], 0
	v_mfma_f32_16x16x32_bf16 v[116:119], v[12:15], v[64:67], 0
	v_mfma_f32_16x16x32_bf16 v[120:123], v[16:19], v[64:67], 0
	ds_read_b128 v[84:87], v238 offset:40960
	ds_read_b128 v[36:39], v220 offset:0
	ds_read_b128 v[40:43], v220 offset:4096
	ds_read_b128 v[88:91], v238 offset:45056
	s_waitcnt lgkmcnt(8)
	v_mfma_f32_16x16x32_bf16 v[108:111], v[20:23], v[68:71], v[108:111]
	v_mfma_f32_16x16x32_bf16 v[112:115], v[24:27], v[68:71], v[112:115]
	v_mfma_f32_16x16x32_bf16 v[116:119], v[20:23], v[72:75], v[116:119]
	v_mfma_f32_16x16x32_bf16 v[120:123], v[24:27], v[72:75], v[120:123]
	ds_read_b128 v[92:95], v231 offset:40960
	ds_read_b128 v[44:47], v219 offset:0
	ds_read_b128 v[48:51], v219 offset:2048
	ds_read_b128 v[96:99], v231 offset:43008
	s_waitcnt lgkmcnt(8)
	v_mfma_f32_16x16x32_bf16 v[108:111], v[28:31], v[76:79], v[108:111]
	v_mfma_f32_16x16x32_bf16 v[112:115], v[32:35], v[76:79], v[112:115]
	v_mfma_f32_16x16x32_bf16 v[116:119], v[28:31], v[80:83], v[116:119]
	v_mfma_f32_16x16x32_bf16 v[120:123], v[32:35], v[80:83], v[120:123]
	ds_read_b128 v[100:103], v230 offset:40960
	ds_read_b128 v[52:55], v218 offset:0
	ds_read_b128 v[56:59], v218 offset:2048
	ds_read_b128 v[104:107], v230 offset:43008
	s_waitcnt lgkmcnt(8)
	v_mfma_f32_16x16x32_bf16 v[108:111], v[36:39], v[84:87], v[108:111]
	v_mfma_f32_16x16x32_bf16 v[112:115], v[40:43], v[84:87], v[112:115]
	v_mfma_f32_16x16x32_bf16 v[116:119], v[36:39], v[88:91], v[116:119]
	v_mfma_f32_16x16x32_bf16 v[120:123], v[40:43], v[88:91], v[120:123]
	s_waitcnt lgkmcnt(4)
	v_mfma_f32_16x16x32_bf16 v[108:111], v[44:47], v[92:95], v[108:111]
	v_mfma_f32_16x16x32_bf16 v[112:115], v[48:51], v[92:95], v[112:115]
	v_mfma_f32_16x16x32_bf16 v[116:119], v[44:47], v[96:99], v[116:119]
	v_mfma_f32_16x16x32_bf16 v[120:123], v[48:51], v[96:99], v[120:123]
	s_waitcnt lgkmcnt(0)
	v_mfma_f32_16x16x32_bf16 v[108:111], v[52:55], v[100:103], v[108:111]
	v_mfma_f32_16x16x32_bf16 v[112:115], v[56:59], v[100:103], v[112:115]
	v_mfma_f32_16x16x32_bf16 v[116:119], v[52:55], v[104:107], v[116:119]
	v_mfma_f32_16x16x32_bf16 v[120:123], v[56:59], v[104:107], v[120:123]
	s_nop 7
	s_nop 7
	v_cvt_pk_bf16_f32 v124, v108, v109
	v_cvt_pk_bf16_f32 v125, v110, v111
	v_cvt_pk_bf16_f32 v126, v112, v113
	v_cvt_pk_bf16_f32 v127, v114, v115
	v_cvt_pk_bf16_f32 v128, v116, v117
	v_cvt_pk_bf16_f32 v129, v118, v119
	v_cvt_pk_bf16_f32 v130, v120, v121
	v_cvt_pk_bf16_f32 v131, v122, v123
	global_store_dwordx2 v248, v[124:125], s[18:19]
	global_store_dwordx2 v248, v[126:127], s[18:19] offset:32
	global_store_dwordx2 v247, v[128:129], s[18:19]
	global_store_dwordx2 v247, v[130:131], s[18:19] offset:32
	s_add_u32 s18, s18, 0x20000
	s_addc_u32 s19, s19, 0
	s_add_i32 s33, s33, 1
	s_waitcnt vmcnt(13)
	s_waitcnt lgkmcnt(0)
	s_barrier
	ds_read_b128 v[60:63], v235 offset:0
	ds_read_b128 v[12:15], v223 offset:12544
	ds_read_b128 v[16:19], v223 offset:16640
	ds_read_b128 v[64:67], v235 offset:4096
	ds_read_b128 v[68:71], v234 offset:0
	ds_read_b128 v[20:23], v222 offset:12544
	ds_read_b128 v[24:27], v222 offset:16640
	ds_read_b128 v[72:75], v234 offset:4096
	ds_read_b128 v[76:79], v233 offset:0
	ds_read_b128 v[28:31], v221 offset:12544
	ds_read_b128 v[32:35], v221 offset:16640
	ds_read_b128 v[80:83], v233 offset:4096
	s_add_i32 m0, s46, 0xa000
	s_nop 0
	global_load_lds_dwordx4 v255, s[8:9]
	s_add_i32 m0, s46, 0xa400
	s_nop 0
	global_load_lds_dwordx4 v254, s[8:9]
	s_add_i32 m0, s47, 0xa000
	s_nop 0
	global_load_lds_dwordx4 v253, s[10:11]
	s_add_i32 m0, s48, 0xa000
	s_nop 0
	global_load_lds_dwordx4 v252, s[12:13]
	s_add_i32 m0, s48, 0xa400
	s_nop 0
	global_load_lds_dwordx4 v251, s[12:13]
	s_cmp_lt_u32 s33, 29
	s_cselect_b32 s43, 0x10000, 0
	s_add_u32 s8, s8, s43
	s_addc_u32 s9, s9, 0
	s_cmp_lt_u32 s33, 29
	s_cselect_b32 s43, 0x2000, 0
	s_add_u32 s10, s10, s43
	s_addc_u32 s11, s11, 0
	s_cmp_lt_u32 s33, 29
	s_cselect_b32 s43, 0x4000, 0
	s_add_u32 s12, s12, s43
	s_addc_u32 s13, s13, 0
	s_waitcnt lgkmcnt(8)
	v_mfma_f32_16x16x32_bf16 v[108:111], v[12:15], v[60:63], 0
	v_mfma_f32_16x16x32_bf16 v[112:115], v[16:19], v[60:63], 0
	v_mfma_f32_16x16x32_bf16 v[116:119], v[12:15], v[64:67], 0
	v_mfma_f32_16x16x32_bf16 v[120:123], v[16:19], v[64:67], 0
	ds_read_b128 v[84:87], v232 offset:0
	ds_read_b128 v[36:39], v220 offset:12544
	ds_read_b128 v[40:43], v220 offset:16640
	ds_read_b128 v[88:91], v232 offset:4096
	s_waitcnt lgkmcnt(8)
; __device__ __forceinline__ void gla_scan_item(const Ctx& C, int item, LAS unsigned char* lds, int tid) {
;     ...
;     SCAN_LOAD(A, 0); SCAN_LOAD(B, 1);
; #pragma unroll
;     for (int n = 0; n < 32; n += 2) { SCAN_STEP(A, n); SCAN_STEP(B, n + 1); }
	v_mfma_f32_16x16x32_bf16 v[108:111], v[20:23], v[68:71], v[108:111]
	v_mfma_f32_16x16x32_bf16 v[112:115], v[24:27], v[68:71], v[112:115]
	v_mfma_f32_16x16x32_bf16 v[116:119], v[20:23], v[72:75], v[116:119]
	v_mfma_f32_16x16x32_bf16 v[120:123], v[24:27], v[72:75], v[120:123]
	ds_read_b128 v[92:95], v229 offset:0
	ds_read_b128 v[44:47], v219 offset:12288
	ds_read_b128 v[48:51], v219 offset:14336
	ds_read_b128 v[96:99], v229 offset:2048
	s_waitcnt lgkmcnt(8)
	v_mfma_f32_16x16x32_bf16 v[108:111], v[28:31], v[76:79], v[108:111]
	v_mfma_f32_16x16x32_bf16 v[112:115], v[32:35], v[76:79], v[112:115]
	v_mfma_f32_16x16x32_bf16 v[116:119], v[28:31], v[80:83], v[116:119]
	v_mfma_f32_16x16x32_bf16 v[120:123], v[32:35], v[80:83], v[120:123]
	ds_read_b128 v[100:103], v228 offset:0
	ds_read_b128 v[52:55], v218 offset:12288
	ds_read_b128 v[56:59], v218 offset:14336
	ds_read_b128 v[104:107], v228 offset:2048
	s_waitcnt lgkmcnt(8)
	v_mfma_f32_16x16x32_bf16 v[108:111], v[36:39], v[84:87], v[108:111]
	v_mfma_f32_16x16x32_bf16 v[112:115], v[40:43], v[84:87], v[112:115]
	v_mfma_f32_16x16x32_bf16 v[116:119], v[36:39], v[88:91], v[116:119]
	v_mfma_f32_16x16x32_bf16 v[120:123], v[40:43], v[88:91], v[120:123]
	s_waitcnt lgkmcnt(4)
	v_mfma_f32_16x16x32_bf16 v[108:111], v[44:47], v[92:95], v[108:111]
	v_mfma_f32_16x16x32_bf16 v[112:115], v[48:51], v[92:95], v[112:115]
	v_mfma_f32_16x16x32_bf16 v[116:119], v[44:47], v[96:99], v[116:119]
	v_mfma_f32_16x16x32_bf16 v[120:123], v[48:51], v[96:99], v[120:123]
	s_waitcnt lgkmcnt(0)
	v_mfma_f32_16x16x32_bf16 v[108:111], v[52:55], v[100:103], v[108:111]
	v_mfma_f32_16x16x32_bf16 v[112:115], v[56:59], v[100:103], v[112:115]
	v_mfma_f32_16x16x32_bf16 v[116:119], v[52:55], v[104:107], v[116:119]
	v_mfma_f32_16x16x32_bf16 v[120:123], v[56:59], v[104:107], v[120:123]
	s_nop 7
	s_nop 7
	v_cvt_pk_bf16_f32 v124, v108, v109
	v_cvt_pk_bf16_f32 v125, v110, v111
	v_cvt_pk_bf16_f32 v126, v112, v113
	v_cvt_pk_bf16_f32 v127, v114, v115
	v_cvt_pk_bf16_f32 v128, v116, v117
	v_cvt_pk_bf16_f32 v129, v118, v119
	v_cvt_pk_bf16_f32 v130, v120, v121
	v_cvt_pk_bf16_f32 v131, v122, v123
	global_store_dwordx2 v248, v[124:125], s[18:19]
	global_store_dwordx2 v248, v[126:127], s[18:19] offset:32
	global_store_dwordx2 v247, v[128:129], s[18:19]
	global_store_dwordx2 v247, v[130:131], s[18:19] offset:32
	s_add_u32 s18, s18, 0x20000
	s_addc_u32 s19, s19, 0
	s_add_i32 s33, s33, 1
	s_waitcnt vmcnt(13)
	s_waitcnt lgkmcnt(0)
	s_barrier
	s_cmp_lt_u32 s33, 30
	s_cbranch_scc1 .Lp3O_loop
	ds_read_b128 v[60:63], v241 offset:0
	ds_read_b128 v[12:15], v223 offset:0
	ds_read_b128 v[16:19], v223 offset:4096
	ds_read_b128 v[64:67], v241 offset:4096
	ds_read_b128 v[68:71], v240 offset:0
	ds_read_b128 v[20:23], v222 offset:0
	ds_read_b128 v[24:27], v222 offset:4096
	ds_read_b128 v[72:75], v240 offset:4096
	ds_read_b128 v[76:79], v239 offset:0
	ds_read_b128 v[28:31], v221 offset:0
	ds_read_b128 v[32:35], v221 offset:4096
	ds_read_b128 v[80:83], v239 offset:4096
	s_add_i32 m0, s46, 0x14000
	s_nop 0
	global_load_lds_dwordx4 v255, s[8:9]
	s_add_i32 m0, s46, 0x14400
	s_nop 0
	global_load_lds_dwordx4 v254, s[8:9]
	s_add_i32 m0, s47, 0x14000
	s_nop 0
	global_load_lds_dwordx4 v253, s[10:11]
	s_add_i32 m0, s48, 0x14000
	s_nop 0
	global_load_lds_dwordx4 v252, s[12:13]
	s_add_i32 m0, s48, 0x14400
	s_nop 0
	global_load_lds_dwordx4 v251, s[12:13]
	s_cmp_lt_u32 s33, 29
	s_cselect_b32 s43, 0x10000, 0
	s_add_u32 s8, s8, s43
	s_addc_u32 s9, s9, 0
	s_cmp_lt_u32 s33, 29
	s_cselect_b32 s43, 0x2000, 0
	s_add_u32 s10, s10, s43
	s_addc_u32 s11, s11, 0
	s_cmp_lt_u32 s33, 29
	s_cselect_b32 s43, 0x4000, 0
	s_add_u32 s12, s12, s43
	s_addc_u32 s13, s13, 0
	s_waitcnt lgkmcnt(8)
	v_mfma_f32_16x16x32_bf16 v[108:111], v[12:15], v[60:63], 0
	v_mfma_f32_16x16x32_bf16 v[112:115], v[16:19], v[60:63], 0
	v_mfma_f32_16x16x32_bf16 v[116:119], v[12:15], v[64:67], 0
	v_mfma_f32_16x16x32_bf16 v[120:123], v[16:19], v[64:67], 0
	ds_read_b128 v[84:87], v238 offset:0
	ds_read_b128 v[36:39], v220 offset:0
	ds_read_b128 v[40:43], v220 offset:4096
	ds_read_b128 v[88:91], v238 offset:4096
	s_waitcnt lgkmcnt(8)
	v_mfma_f32_16x16x32_bf16 v[108:111], v[20:23], v[68:71], v[108:111]
	v_mfma_f32_16x16x32_bf16 v[112:115], v[24:27], v[68:71], v[112:115]
	v_mfma_f32_16x16x32_bf16 v[116:119], v[20:23], v[72:75], v[116:119]
	v_mfma_f32_16x16x32_bf16 v[120:123], v[24:27], v[72:75], v[120:123]
	ds_read_b128 v[92:95], v231 offset:0
	ds_read_b128 v[44:47], v219 offset:0
	ds_read_b128 v[48:51], v219 offset:2048
	ds_read_b128 v[96:99], v231 offset:2048
	s_waitcnt lgkmcnt(8)
	v_mfma_f32_16x16x32_bf16 v[108:111], v[28:31], v[76:79], v[108:111]
	v_mfma_f32_16x16x32_bf16 v[112:115], v[32:35], v[76:79], v[112:115]
	v_mfma_f32_16x16x32_bf16 v[116:119], v[28:31], v[80:83], v[116:119]
	v_mfma_f32_16x16x32_bf16 v[120:123], v[32:35], v[80:83], v[120:123]
	ds_read_b128 v[100:103], v230 offset:0
	ds_read_b128 v[52:55], v218 offset:0
	ds_read_b128 v[56:59], v218 offset:2048
	ds_read_b128 v[104:107], v230 offset:2048
	s_waitcnt lgkmcnt(8)
	v_mfma_f32_16x16x32_bf16 v[108:111], v[36:39], v[84:87], v[108:111]
	v_mfma_f32_16x16x32_bf16 v[112:115], v[40:43], v[84:87], v[112:115]
	v_mfma_f32_16x16x32_bf16 v[116:119], v[36:39], v[88:91], v[116:119]
	v_mfma_f32_16x16x32_bf16 v[120:123], v[40:43], v[88:91], v[120:123]
	s_waitcnt lgkmcnt(4)
	v_mfma_f32_16x16x32_bf16 v[108:111], v[44:47], v[92:95], v[108:111]
	v_mfma_f32_16x16x32_bf16 v[112:115], v[48:51], v[92:95], v[112:115]
	v_mfma_f32_16x16x32_bf16 v[116:119], v[44:47], v[96:99], v[116:119]
	v_mfma_f32_16x16x32_bf16 v[120:123], v[48:51], v[96:99], v[120:123]
	s_waitcnt lgkmcnt(0)
	v_mfma_f32_16x16x32_bf16 v[108:111], v[52:55], v[100:103], v[108:111]
	v_mfma_f32_16x16x32_bf16 v[112:115], v[56:59], v[100:103], v[112:115]
	v_mfma_f32_16x16x32_bf16 v[116:119], v[52:55], v[104:107], v[116:119]
	v_mfma_f32_16x16x32_bf16 v[120:123], v[56:59], v[104:107], v[120:123]
	s_nop 7
	s_nop 7
	v_cvt_pk_bf16_f32 v124, v108, v109
	v_cvt_pk_bf16_f32 v125, v110, v111
	v_cvt_pk_bf16_f32 v126, v112, v113
	v_cvt_pk_bf16_f32 v127, v114, v115
	v_cvt_pk_bf16_f32 v128, v116, v117
	v_cvt_pk_bf16_f32 v129, v118, v119
	v_cvt_pk_bf16_f32 v130, v120, v121
	v_cvt_pk_bf16_f32 v131, v122, v123
	global_store_dwordx2 v248, v[124:125], s[18:19]
	global_store_dwordx2 v248, v[126:127], s[18:19] offset:32
	global_store_dwordx2 v247, v[128:129], s[18:19]
	global_store_dwordx2 v247, v[130:131], s[18:19] offset:32
	s_add_u32 s18, s18, 0x20000
	s_addc_u32 s19, s19, 0
	s_add_i32 s33, s33, 1
	s_waitcnt vmcnt(13)
	s_waitcnt lgkmcnt(0)
	s_barrier
; __device__ __forceinline__ void gla_scan_item(const Ctx& C, int item, LAS unsigned char* lds, int tid) {
;     ...
;     SCAN_LOAD(A, 0); SCAN_LOAD(B, 1);
; #pragma unroll
;     for (int n = 0; n < 32; n += 2) { SCAN_STEP(A, n); SCAN_STEP(B, n + 1); }
	ds_read_b128 v[60:63], v241 offset:40960
	ds_read_b128 v[12:15], v223 offset:12544
	ds_read_b128 v[16:19], v223 offset:16640
	ds_read_b128 v[64:67], v241 offset:45056
	ds_read_b128 v[68:71], v240 offset:40960
	ds_read_b128 v[20:23], v222 offset:12544
	ds_read_b128 v[24:27], v222 offset:16640
	ds_read_b128 v[72:75], v240 offset:45056
	ds_read_b128 v[76:79], v239 offset:40960
	ds_read_b128 v[28:31], v221 offset:12544
	ds_read_b128 v[32:35], v221 offset:16640
	ds_read_b128 v[80:83], v239 offset:45056
	s_mov_b32 m0, s46
	s_nop 0
	global_load_lds_dwordx4 v255, s[8:9]
	s_add_i32 m0, s46, 0x400
	s_nop 0
	global_load_lds_dwordx4 v254, s[8:9]
	s_mov_b32 m0, s47
	s_nop 0
	global_load_lds_dwordx4 v253, s[10:11]
	s_mov_b32 m0, s48
	s_nop 0
	global_load_lds_dwordx4 v252, s[12:13]
	s_add_i32 m0, s48, 0x400
	s_nop 0
	global_load_lds_dwordx4 v251, s[12:13]
	s_cmp_lt_u32 s33, 29
	s_cselect_b32 s43, 0x10000, 0
	s_add_u32 s8, s8, s43
	s_addc_u32 s9, s9, 0
	s_cmp_lt_u32 s33, 29
	s_cselect_b32 s43, 0x2000, 0
	s_add_u32 s10, s10, s43
	s_addc_u32 s11, s11, 0
	s_cmp_lt_u32 s33, 29
	s_cselect_b32 s43, 0x4000, 0
	s_add_u32 s12, s12, s43
	s_addc_u32 s13, s13, 0
	s_waitcnt lgkmcnt(8)
	v_mfma_f32_16x16x32_bf16 v[108:111], v[12:15], v[60:63], 0
	v_mfma_f32_16x16x32_bf16 v[112:115], v[16:19], v[60:63], 0
	v_mfma_f32_16x16x32_bf16 v[116:119], v[12:15], v[64:67], 0
	v_mfma_f32_16x16x32_bf16 v[120:123], v[16:19], v[64:67], 0
	ds_read_b128 v[84:87], v238 offset:40960
	ds_read_b128 v[36:39], v220 offset:12544
	ds_read_b128 v[40:43], v220 offset:16640
	ds_read_b128 v[88:91], v238 offset:45056
	s_waitcnt lgkmcnt(8)
	v_mfma_f32_16x16x32_bf16 v[108:111], v[20:23], v[68:71], v[108:111]
	v_mfma_f32_16x16x32_bf16 v[112:115], v[24:27], v[68:71], v[112:115]
	v_mfma_f32_16x16x32_bf16 v[116:119], v[20:23], v[72:75], v[116:119]
	v_mfma_f32_16x16x32_bf16 v[120:123], v[24:27], v[72:75], v[120:123]
	ds_read_b128 v[92:95], v231 offset:40960
	ds_read_b128 v[44:47], v219 offset:12288
	ds_read_b128 v[48:51], v219 offset:14336
	ds_read_b128 v[96:99], v231 offset:43008
	s_waitcnt lgkmcnt(8)
	v_mfma_f32_16x16x32_bf16 v[108:111], v[28:31], v[76:79], v[108:111]
	v_mfma_f32_16x16x32_bf16 v[112:115], v[32:35], v[76:79], v[112:115]
	v_mfma_f32_16x16x32_bf16 v[116:119], v[28:31], v[80:83], v[116:119]
	v_mfma_f32_16x16x32_bf16 v[120:123], v[32:35], v[80:83], v[120:123]
	ds_read_b128 v[100:103], v230 offset:40960
	ds_read_b128 v[52:55], v218 offset:12288
	ds_read_b128 v[56:59], v218 offset:14336
	ds_read_b128 v[104:107], v230 offset:43008
	s_waitcnt lgkmcnt(8)
	v_mfma_f32_16x16x32_bf16 v[108:111], v[36:39], v[84:87], v[108:111]
	v_mfma_f32_16x16x32_bf16 v[112:115], v[40:43], v[84:87], v[112:115]
	v_mfma_f32_16x16x32_bf16 v[116:119], v[36:39], v[88:91], v[116:119]
	v_mfma_f32_16x16x32_bf16 v[120:123], v[40:43], v[88:91], v[120:123]
	s_waitcnt lgkmcnt(4)
	v_mfma_f32_16x16x32_bf16 v[108:111], v[44:47], v[92:95], v[108:111]
	v_mfma_f32_16x16x32_bf16 v[112:115], v[48:51], v[92:95], v[112:115]
	v_mfma_f32_16x16x32_bf16 v[116:119], v[44:47], v[96:99], v[116:119]
	v_mfma_f32_16x16x32_bf16 v[120:123], v[48:51], v[96:99], v[120:123]
	s_waitcnt lgkmcnt(0)
	v_mfma_f32_16x16x32_bf16 v[108:111], v[52:55], v[100:103], v[108:111]
	v_mfma_f32_16x16x32_bf16 v[112:115], v[56:59], v[100:103], v[112:115]
	v_mfma_f32_16x16x32_bf16 v[116:119], v[52:55], v[104:107], v[116:119]
	v_mfma_f32_16x16x32_bf16 v[120:123], v[56:59], v[104:107], v[120:123]
	s_nop 7
	s_nop 7
	v_cvt_pk_bf16_f32 v124, v108, v109
	v_cvt_pk_bf16_f32 v125, v110, v111
	v_cvt_pk_bf16_f32 v126, v112, v113
	v_cvt_pk_bf16_f32 v127, v114, v115
	v_cvt_pk_bf16_f32 v128, v116, v117
	v_cvt_pk_bf16_f32 v129, v118, v119
	v_cvt_pk_bf16_f32 v130, v120, v121
	v_cvt_pk_bf16_f32 v131, v122, v123
	global_store_dwordx2 v248, v[124:125], s[18:19]
	global_store_dwordx2 v248, v[126:127], s[18:19] offset:32
	global_store_dwordx2 v247, v[128:129], s[18:19]
	global_store_dwordx2 v247, v[130:131], s[18:19] offset:32
	s_add_u32 s18, s18, 0x20000
	s_addc_u32 s19, s19, 0
	s_add_i32 s33, s33, 1
	s_waitcnt vmcnt(13)
	s_waitcnt lgkmcnt(0)
	s_barrier
	s_waitcnt vmcnt(0) lgkmcnt(0)
	s_barrier
	s_add_i32 s3, s3, s42
	s_cmpk_lt_i32 s3, 0x100
	s_cbranch_scc1 .Lp3O_item
	s_branch .Lp3_done

; #define LAS __attribute__((address_space(3)))
; __device__ __forceinline__ void gla_scan_item(const Ctx& C, int item, LAS unsigned char* lds, int tid) {
;     const int jx = item >> 3, bh = (item & 7) * 4 + (jx >> 3), sl = jx & 7, b = bh >> 2, h = bh & 3;
;     LAS bf16* Aq = (LAS bf16*)lds;
;     LAS bf16* Bc = (LAS bf16*)(lds + 25600);
;     LAS bf16* Kt = (LAS bf16*)(lds + 38400);
;     const int wave = tid >> 6, lane = tid & 63, l15 = lane & 15, quad = lane >> 4;
;     f32x4 S[2] = {(f32x4){0.f, 0.f, 0.f, 0.f}, (f32x4){0.f, 0.f, 0.f, 0.f}};
;     *(LAS u32x4*)(Bc + (tid >> 4) * 200 + (tid & 15) * 8) = (u32x4){0u, 0u, 0u, 0u};
;     u32x4 rq0A, rq1A, rsA, rk0A, rk1A, rvA = (u32x4){0u, 0u, 0u, 0u}; f32x4 rdA;
;     u32x4 rq0B, rq1B, rsB, rk0B, rk1B, rvB = (u32x4){0u, 0u, 0u, 0u}; f32x4 rdB;
.Lp3S_item:
	s_lshr_b32 s4, s3, 3
	s_and_b32 s41, s4, 7
	s_lshr_b32 s5, s4, 3
	s_and_b32 s37, s3, 7
	s_lshl_b32 s37, s37, 2
	s_add_i32 s37, s37, s5
	s_lshr_b32 s39, s37, 2
	s_and_b32 s40, s37, 3
	s_add_u32 s8, s94, 0x1d800000
	s_addc_u32 s9, s95, 0
	s_lshl_b32 s31, s39, 21
	s_add_u32 s8, s8, s31
	s_addc_u32 s9, s9, 0
	s_lshl_b32 s31, s40, 8
	s_add_u32 s8, s8, s31
	s_addc_u32 s9, s9, 0
	s_add_u32 s10, s94, 0x2f00000
	s_addc_u32 s11, s95, 0
	s_lshl_b32 s31, s37, 18
	s_add_u32 s10, s10, s31
	s_addc_u32 s11, s11, 0
	s_add_u32 s12, s94, 0x3700000
	s_addc_u32 s13, s95, 0
	s_lshl_b32 s31, s37, 19
	s_add_u32 s12, s12, s31
	s_addc_u32 s13, s13, 0
	s_add_u32 s16, s94, 0x2e00000
	s_addc_u32 s17, s95, 0
	s_lshl_b32 s31, s37, 14
	s_add_u32 s16, s16, s31
	s_addc_u32 s17, s17, 0
	s_add_u32 s34, s92, 0x4090000
	s_addc_u32 s35, s93, 0
	s_lshl_b32 s31, s37, 17
	s_add_u32 s34, s34, s31
	s_addc_u32 s35, s35, 0
	s_lshl_b32 s31, s41, 7
	s_add_u32 s34, s34, s31
	s_addc_u32 s35, s35, 0
	v_mov_b32_e32 v60, 0
	v_mov_b32_e32 v61, 0
	v_mov_b32_e32 v62, 0
	v_mov_b32_e32 v63, 0
	v_mov_b32_e32 v64, 0
	v_mov_b32_e32 v65, 0
	v_mov_b32_e32 v66, 0
	v_mov_b32_e32 v67, 0
	v_mov_b32_e32 v68, 0
	v_mov_b32_e32 v69, 0
	v_mov_b32_e32 v70, 0
	v_mov_b32_e32 v71, 0
	v_mov_b32_e32 v72, 0
	v_mov_b32_e32 v73, 0
	v_mov_b32_e32 v74, 0
	v_mov_b32_e32 v75, 0
	v_mov_b32_e32 v76, 0
	v_mov_b32_e32 v77, 0
	v_mov_b32_e32 v78, 0
	v_mov_b32_e32 v79, 0
	v_mov_b32_e32 v80, 0
	v_mov_b32_e32 v81, 0
	v_mov_b32_e32 v82, 0
	v_mov_b32_e32 v83, 0
	v_mov_b32_e32 v84, 0
	v_mov_b32_e32 v85, 0
	v_mov_b32_e32 v86, 0
	v_mov_b32_e32 v87, 0
	v_mov_b32_e32 v88, 0
	v_mov_b32_e32 v89, 0
	v_mov_b32_e32 v90, 0
	v_mov_b32_e32 v91, 0
	ds_write_b128 v246, v[8:11]
	s_mov_b32 m0, s46
	s_nop 0
	global_load_lds_dwordx4 v255, s[8:9]
	s_add_i32 m0, s46, 0x400
	s_nop 0
	global_load_lds_dwordx4 v254, s[8:9]
	s_mov_b32 m0, s47
	s_nop 0
	global_load_lds_dwordx4 v253, s[10:11]
	s_mov_b32 m0, s48
	s_nop 0
	global_load_lds_dwordx4 v252, s[12:13]
	s_add_i32 m0, s48, 0x400
	s_nop 0
	global_load_lds_dwordx4 v251, s[12:13]
	s_add_u32 s8, s8, 0x10000
	s_addc_u32 s9, s9, 0
	s_add_u32 s10, s10, 0x2000
	s_addc_u32 s11, s11, 0
	s_add_u32 s12, s12, 0x4000
	s_addc_u32 s13, s13, 0
	s_add_i32 m0, s46, 0xa000
	s_nop 0
	global_load_lds_dwordx4 v255, s[8:9]
	s_add_i32 m0, s46, 0xa400
	s_nop 0
	global_load_lds_dwordx4 v254, s[8:9]
	s_add_i32 m0, s47, 0xa000
	s_nop 0
	global_load_lds_dwordx4 v253, s[10:11]
	s_add_i32 m0, s48, 0xa000
	s_nop 0
	global_load_lds_dwordx4 v252, s[12:13]
	s_add_i32 m0, s48, 0xa400
	s_nop 0
	global_load_lds_dwordx4 v251, s[12:13]
	s_add_u32 s8, s8, 0x10000
	s_addc_u32 s9, s9, 0
	s_add_u32 s10, s10, 0x2000
	s_addc_u32 s11, s11, 0
	s_add_u32 s12, s12, 0x4000
	s_addc_u32 s13, s13, 0
	global_load_dwordx4 v[92:95], v249, s[16:17] offset:0
	global_load_dwordx4 v[96:99], v249, s[16:17] offset:64
	global_load_dwordx4 v[100:103], v249, s[16:17] offset:128
	global_load_dwordx4 v[104:107], v249, s[16:17] offset:192
	s_add_u32 s16, s16, 0x200
	s_addc_u32 s17, s17, 0
	global_load_dwordx4 v[108:111], v249, s[16:17] offset:0
	global_load_dwordx4 v[112:115], v249, s[16:17] offset:64
	global_load_dwordx4 v[116:119], v249, s[16:17] offset:128
	global_load_dwordx4 v[120:123], v249, s[16:17] offset:192
	s_add_u32 s16, s16, 0x200
	s_addc_u32 s17, s17, 0
	global_load_dwordx4 v[124:127], v249, s[16:17] offset:0
	global_load_dwordx4 v[128:131], v249, s[16:17] offset:64
	global_load_dwordx4 v[132:135], v249, s[16:17] offset:128
	global_load_dwordx4 v[136:139], v249, s[16:17] offset:192
	s_add_u32 s16, s16, 0x200
	s_addc_u32 s17, s17, 0
	s_waitcnt vmcnt(0)
	s_mov_b32 s33, 0
	s_waitcnt lgkmcnt(0)
	s_barrier
.Lp3S_loop:
	ds_read_b128 v[44:47], v217 offset:0
	ds_read_b128 v[48:51], v217 offset:2048
	ds_read_b128 v[12:15], v227 offset:0
	ds_read_b128 v[16:19], v227 offset:2048
	ds_read_b128 v[20:23], v227 offset:4096
	ds_read_b128 v[24:27], v227 offset:6144
	ds_read_b128 v[52:55], v216 offset:0
	ds_read_b128 v[56:59], v216 offset:2048
	ds_read_b128 v[28:31], v226 offset:0
	ds_read_b128 v[32:35], v226 offset:2048
	ds_read_b128 v[36:39], v226 offset:4096
	ds_read_b128 v[40:43], v226 offset:6144
	s_waitcnt vmcnt(18)
	v_pk_mul_f32 v[60:61], v[60:61], v[92:93]
	v_pk_mul_f32 v[62:63], v[62:63], v[94:95]
	v_pk_mul_f32 v[64:65], v[64:65], v[92:93]
	v_pk_mul_f32 v[66:67], v[66:67], v[94:95]
	v_pk_mul_f32 v[68:69], v[68:69], v[96:97]
	v_pk_mul_f32 v[70:71], v[70:71], v[98:99]
	v_pk_mul_f32 v[72:73], v[72:73], v[96:97]
	v_pk_mul_f32 v[74:75], v[74:75], v[98:99]
	v_pk_mul_f32 v[76:77], v[76:77], v[100:101]
	v_pk_mul_f32 v[78:79], v[78:79], v[102:103]
	v_pk_mul_f32 v[80:81], v[80:81], v[100:101]
	v_pk_mul_f32 v[82:83], v[82:83], v[102:103]
	v_pk_mul_f32 v[84:85], v[84:85], v[104:105]
	v_pk_mul_f32 v[86:87], v[86:87], v[106:107]
	v_pk_mul_f32 v[88:89], v[88:89], v[104:105]
	v_pk_mul_f32 v[90:91], v[90:91], v[106:107]
	s_add_i32 m0, s46, 0x14000
	s_nop 0
	global_load_lds_dwordx4 v255, s[8:9]
	s_add_i32 m0, s46, 0x14400
	s_nop 0
	global_load_lds_dwordx4 v254, s[8:9]
	s_add_i32 m0, s47, 0x14000
	s_nop 0
	global_load_lds_dwordx4 v253, s[10:11]
	s_add_i32 m0, s48, 0x14000
	s_nop 0
	global_load_lds_dwordx4 v252, s[12:13]
	s_add_i32 m0, s48, 0x14400
	s_nop 0
	global_load_lds_dwordx4 v251, s[12:13]
	s_cmp_lt_u32 s33, 29
	s_cselect_b32 s43, 0x10000, 0
	s_add_u32 s8, s8, s43
	s_addc_u32 s9, s9, 0
	s_cmp_lt_u32 s33, 29
	s_cselect_b32 s43, 0x2000, 0
	s_add_u32 s10, s10, s43
	s_addc_u32 s11, s11, 0
	s_cmp_lt_u32 s33, 29
	s_cselect_b32 s43, 0x4000, 0
	s_add_u32 s12, s12, s43
	s_addc_u32 s13, s13, 0
	s_waitcnt lgkmcnt(6)
	v_mfma_f32_16x16x32_bf16 v[60:63], v[12:15], v[44:47], v[60:63]
	v_mfma_f32_16x16x32_bf16 v[64:67], v[12:15], v[48:51], v[64:67]
	v_mfma_f32_16x16x32_bf16 v[68:71], v[16:19], v[44:47], v[68:71]
	v_mfma_f32_16x16x32_bf16 v[72:75], v[16:19], v[48:51], v[72:75]
	v_mfma_f32_16x16x32_bf16 v[76:79], v[20:23], v[44:47], v[76:79]
	v_mfma_f32_16x16x32_bf16 v[80:83], v[20:23], v[48:51], v[80:83]
	v_mfma_f32_16x16x32_bf16 v[84:87], v[24:27], v[44:47], v[84:87]
	v_mfma_f32_16x16x32_bf16 v[88:91], v[24:27], v[48:51], v[88:91]
	s_waitcnt lgkmcnt(0)
	v_mfma_f32_16x16x32_bf16 v[60:63], v[28:31], v[52:55], v[60:63]
	v_mfma_f32_16x16x32_bf16 v[64:67], v[28:31], v[56:59], v[64:67]
	v_mfma_f32_16x16x32_bf16 v[68:71], v[32:35], v[52:55], v[68:71]
	v_mfma_f32_16x16x32_bf16 v[72:75], v[32:35], v[56:59], v[72:75]
	v_mfma_f32_16x16x32_bf16 v[76:79], v[36:39], v[52:55], v[76:79]
	v_mfma_f32_16x16x32_bf16 v[80:83], v[36:39], v[56:59], v[80:83]
	v_mfma_f32_16x16x32_bf16 v[84:87], v[40:43], v[52:55], v[84:87]
	v_mfma_f32_16x16x32_bf16 v[88:91], v[40:43], v[56:59], v[88:91]
	s_nop 3
	global_load_dwordx4 v[92:95], v249, s[16:17] offset:0
	global_load_dwordx4 v[96:99], v249, s[16:17] offset:64
	global_load_dwordx4 v[100:103], v249, s[16:17] offset:128
	global_load_dwordx4 v[104:107], v249, s[16:17] offset:192
	s_cmp_lt_u32 s33, 28
	s_cselect_b32 s43, 0x200, 0
	s_add_u32 s16, s16, s43
	s_addc_u32 s17, s17, 0
	s_add_i32 s33, s33, 1
	s_nop 7
	s_nop 7
	v_cvt_pk_bf16_f32 v140, v60, v61
	v_cvt_pk_bf16_f32 v141, v62, v63
	ds_write_b64 v215, v[140:141] offset:12544
	v_cvt_pk_bf16_f32 v144, v64, v65
	v_cvt_pk_bf16_f32 v145, v66, v67
	ds_write_b64 v215, v[144:145] offset:16640
	s_nop 1
	v_cvt_pk_bf16_f32 v140, v68, v69
	v_cvt_pk_bf16_f32 v141, v70, v71
	ds_write_b64 v214, v[140:141] offset:12544
	v_cvt_pk_bf16_f32 v144, v72, v73
	v_cvt_pk_bf16_f32 v145, v74, v75
	ds_write_b64 v214, v[144:145] offset:16640
	s_nop 1
	v_cvt_pk_bf16_f32 v140, v76, v77
	v_cvt_pk_bf16_f32 v141, v78, v79
	ds_write_b64 v213, v[140:141] offset:12544
	v_cvt_pk_bf16_f32 v144, v80, v81
	v_cvt_pk_bf16_f32 v145, v82, v83
	ds_write_b64 v213, v[144:145] offset:16640
	s_nop 1
	v_cvt_pk_bf16_f32 v140, v84, v85
	v_cvt_pk_bf16_f32 v141, v86, v87
	ds_write_b64 v212, v[140:141] offset:12544
	v_cvt_pk_bf16_f32 v144, v88, v89
	v_cvt_pk_bf16_f32 v145, v90, v91
	ds_write_b64 v212, v[144:145] offset:16640
	s_nop 1
	s_waitcnt vmcnt(13)
	s_waitcnt lgkmcnt(0)
	s_barrier
	ds_read_b128 v[44:47], v217 offset:12288
	ds_read_b128 v[48:51], v217 offset:14336
	ds_read_b128 v[12:15], v227 offset:40960
	ds_read_b128 v[16:19], v227 offset:43008
	ds_read_b128 v[20:23], v227 offset:45056
	ds_read_b128 v[24:27], v227 offset:47104
	ds_read_b128 v[52:55], v216 offset:12288
	ds_read_b128 v[56:59], v216 offset:14336
	ds_read_b128 v[28:31], v226 offset:40960
	ds_read_b128 v[32:35], v226 offset:43008
	ds_read_b128 v[36:39], v226 offset:45056
	ds_read_b128 v[40:43], v226 offset:47104
	s_waitcnt vmcnt(18)
	v_pk_mul_f32 v[60:61], v[60:61], v[108:109]
	v_pk_mul_f32 v[62:63], v[62:63], v[110:111]
	v_pk_mul_f32 v[64:65], v[64:65], v[108:109]
	v_pk_mul_f32 v[66:67], v[66:67], v[110:111]
	v_pk_mul_f32 v[68:69], v[68:69], v[112:113]
	v_pk_mul_f32 v[70:71], v[70:71], v[114:115]
	v_pk_mul_f32 v[72:73], v[72:73], v[112:113]
	v_pk_mul_f32 v[74:75], v[74:75], v[114:115]
	v_pk_mul_f32 v[76:77], v[76:77], v[116:117]
	v_pk_mul_f32 v[78:79], v[78:79], v[118:119]
	v_pk_mul_f32 v[80:81], v[80:81], v[116:117]
	v_pk_mul_f32 v[82:83], v[82:83], v[118:119]
	v_pk_mul_f32 v[84:85], v[84:85], v[120:121]
	v_pk_mul_f32 v[86:87], v[86:87], v[122:123]
	v_pk_mul_f32 v[88:89], v[88:89], v[120:121]
	v_pk_mul_f32 v[90:91], v[90:91], v[122:123]
	s_mov_b32 m0, s46
	s_nop 0
	global_load_lds_dwordx4 v255, s[8:9]
	s_add_i32 m0, s46, 0x400
	s_nop 0
	global_load_lds_dwordx4 v254, s[8:9]
	s_mov_b32 m0, s47
	s_nop 0
	global_load_lds_dwordx4 v253, s[10:11]
	s_mov_b32 m0, s48
	s_nop 0
	global_load_lds_dwordx4 v252, s[12:13]
	s_add_i32 m0, s48, 0x400
	s_nop 0
	global_load_lds_dwordx4 v251, s[12:13]
	s_cmp_lt_u32 s33, 29
	s_cselect_b32 s43, 0x10000, 0
	s_add_u32 s8, s8, s43
	s_addc_u32 s9, s9, 0
	s_cmp_lt_u32 s33, 29
	s_cselect_b32 s43, 0x2000, 0
	s_add_u32 s10, s10, s43
	s_addc_u32 s11, s11, 0
	s_cmp_lt_u32 s33, 29
	s_cselect_b32 s43, 0x4000, 0
	s_add_u32 s12, s12, s43
	s_addc_u32 s13, s13, 0
	s_waitcnt lgkmcnt(6)
	v_mfma_f32_16x16x32_bf16 v[60:63], v[12:15], v[44:47], v[60:63]
	v_mfma_f32_16x16x32_bf16 v[64:67], v[12:15], v[48:51], v[64:67]
	v_mfma_f32_16x16x32_bf16 v[68:71], v[16:19], v[44:47], v[68:71]
	v_mfma_f32_16x16x32_bf16 v[72:75], v[16:19], v[48:51], v[72:75]
	v_mfma_f32_16x16x32_bf16 v[76:79], v[20:23], v[44:47], v[76:79]
	v_mfma_f32_16x16x32_bf16 v[80:83], v[20:23], v[48:51], v[80:83]
	v_mfma_f32_16x16x32_bf16 v[84:87], v[24:27], v[44:47], v[84:87]
	v_mfma_f32_16x16x32_bf16 v[88:91], v[24:27], v[48:51], v[88:91]
	s_waitcnt lgkmcnt(0)
	v_mfma_f32_16x16x32_bf16 v[60:63], v[28:31], v[52:55], v[60:63]
	v_mfma_f32_16x16x32_bf16 v[64:67], v[28:31], v[56:59], v[64:67]
	v_mfma_f32_16x16x32_bf16 v[68:71], v[32:35], v[52:55], v[68:71]
	v_mfma_f32_16x16x32_bf16 v[72:75], v[32:35], v[56:59], v[72:75]
	v_mfma_f32_16x16x32_bf16 v[76:79], v[36:39], v[52:55], v[76:79]
	v_mfma_f32_16x16x32_bf16 v[80:83], v[36:39], v[56:59], v[80:83]
	v_mfma_f32_16x16x32_bf16 v[84:87], v[40:43], v[52:55], v[84:87]
	v_mfma_f32_16x16x32_bf16 v[88:91], v[40:43], v[56:59], v[88:91]
	s_nop 3
	global_load_dwordx4 v[108:111], v249, s[16:17] offset:0
	global_load_dwordx4 v[112:115], v249, s[16:17] offset:64
	global_load_dwordx4 v[116:119], v249, s[16:17] offset:128
	global_load_dwordx4 v[120:123], v249, s[16:17] offset:192
	s_cmp_lt_u32 s33, 28
	s_cselect_b32 s43, 0x200, 0
	s_add_u32 s16, s16, s43
	s_addc_u32 s17, s17, 0
	s_add_i32 s33, s33, 1
	s_nop 7
	s_nop 7
	v_cvt_pk_bf16_f32 v140, v60, v61
	v_cvt_pk_bf16_f32 v141, v62, v63
	ds_write_b64 v215, v[140:141] offset:0
	v_cvt_pk_bf16_f32 v144, v64, v65
	v_cvt_pk_bf16_f32 v145, v66, v67
	ds_write_b64 v215, v[144:145] offset:4096
	s_nop 1
	v_cvt_pk_bf16_f32 v140, v68, v69
	v_cvt_pk_bf16_f32 v141, v70, v71
	ds_write_b64 v214, v[140:141] offset:0
	v_cvt_pk_bf16_f32 v144, v72, v73
	v_cvt_pk_bf16_f32 v145, v74, v75
	ds_write_b64 v214, v[144:145] offset:4096
	s_nop 1
	v_cvt_pk_bf16_f32 v140, v76, v77
	v_cvt_pk_bf16_f32 v141, v78, v79
	ds_write_b64 v213, v[140:141] offset:0
	v_cvt_pk_bf16_f32 v144, v80, v81
	v_cvt_pk_bf16_f32 v145, v82, v83
	ds_write_b64 v213, v[144:145] offset:4096
	s_nop 1
	v_cvt_pk_bf16_f32 v140, v84, v85
	v_cvt_pk_bf16_f32 v141, v86, v87
	ds_write_b64 v212, v[140:141] offset:0
	v_cvt_pk_bf16_f32 v144, v88, v89
	v_cvt_pk_bf16_f32 v145, v90, v91
	ds_write_b64 v212, v[144:145] offset:4096
	s_nop 1
	s_waitcnt vmcnt(13)
	s_waitcnt lgkmcnt(0)
	s_barrier
	ds_read_b128 v[44:47], v217 offset:0
	ds_read_b128 v[48:51], v217 offset:2048
	ds_read_b128 v[12:15], v225 offset:0
	ds_read_b128 v[16:19], v225 offset:2048
	ds_read_b128 v[20:23], v225 offset:4096
	ds_read_b128 v[24:27], v225 offset:6144
	ds_read_b128 v[52:55], v216 offset:0
	ds_read_b128 v[56:59], v216 offset:2048
	ds_read_b128 v[28:31], v224 offset:0
	ds_read_b128 v[32:35], v224 offset:2048
	ds_read_b128 v[36:39], v224 offset:4096
	ds_read_b128 v[40:43], v224 offset:6144
	s_waitcnt vmcnt(18)
	v_pk_mul_f32 v[60:61], v[60:61], v[124:125]
	v_pk_mul_f32 v[62:63], v[62:63], v[126:127]
	v_pk_mul_f32 v[64:65], v[64:65], v[124:125]
	v_pk_mul_f32 v[66:67], v[66:67], v[126:127]
	v_pk_mul_f32 v[68:69], v[68:69], v[128:129]
	v_pk_mul_f32 v[70:71], v[70:71], v[130:131]
	v_pk_mul_f32 v[72:73], v[72:73], v[128:129]
	v_pk_mul_f32 v[74:75], v[74:75], v[130:131]
	v_pk_mul_f32 v[76:77], v[76:77], v[132:133]
	v_pk_mul_f32 v[78:79], v[78:79], v[134:135]
	v_pk_mul_f32 v[80:81], v[80:81], v[132:133]
	v_pk_mul_f32 v[82:83], v[82:83], v[134:135]
	v_pk_mul_f32 v[84:85], v[84:85], v[136:137]
	v_pk_mul_f32 v[86:87], v[86:87], v[138:139]
	v_pk_mul_f32 v[88:89], v[88:89], v[136:137]
	v_pk_mul_f32 v[90:91], v[90:91], v[138:139]
	s_add_i32 m0, s46, 0xa000
	s_nop 0
	global_load_lds_dwordx4 v255, s[8:9]
	s_add_i32 m0, s46, 0xa400
	s_nop 0
	global_load_lds_dwordx4 v254, s[8:9]
	s_add_i32 m0, s47, 0xa000
	s_nop 0
	global_load_lds_dwordx4 v253, s[10:11]
	s_add_i32 m0, s48, 0xa000
	s_nop 0
	global_load_lds_dwordx4 v252, s[12:13]
	s_add_i32 m0, s48, 0xa400
	s_nop 0
	global_load_lds_dwordx4 v251, s[12:13]
	s_cmp_lt_u32 s33, 29
	s_cselect_b32 s43, 0x10000, 0
	s_add_u32 s8, s8, s43
	s_addc_u32 s9, s9, 0
	s_cmp_lt_u32 s33, 29
	s_cselect_b32 s43, 0x2000, 0
	s_add_u32 s10, s10, s43
	s_addc_u32 s11, s11, 0
	s_cmp_lt_u32 s33, 29
	s_cselect_b32 s43, 0x4000, 0
	s_add_u32 s12, s12, s43
	s_addc_u32 s13, s13, 0
	s_waitcnt lgkmcnt(6)
	v_mfma_f32_16x16x32_bf16 v[60:63], v[12:15], v[44:47], v[60:63]
	v_mfma_f32_16x16x32_bf16 v[64:67], v[12:15], v[48:51], v[64:67]
	v_mfma_f32_16x16x32_bf16 v[68:71], v[16:19], v[44:47], v[68:71]
	v_mfma_f32_16x16x32_bf16 v[72:75], v[16:19], v[48:51], v[72:75]
	v_mfma_f32_16x16x32_bf16 v[76:79], v[20:23], v[44:47], v[76:79]
	v_mfma_f32_16x16x32_bf16 v[80:83], v[20:23], v[48:51], v[80:83]
	v_mfma_f32_16x16x32_bf16 v[84:87], v[24:27], v[44:47], v[84:87]
	v_mfma_f32_16x16x32_bf16 v[88:91], v[24:27], v[48:51], v[88:91]
	s_waitcnt lgkmcnt(0)
	v_mfma_f32_16x16x32_bf16 v[60:63], v[28:31], v[52:55], v[60:63]
	v_mfma_f32_16x16x32_bf16 v[64:67], v[28:31], v[56:59], v[64:67]
	v_mfma_f32_16x16x32_bf16 v[68:71], v[32:35], v[52:55], v[68:71]
	v_mfma_f32_16x16x32_bf16 v[72:75], v[32:35], v[56:59], v[72:75]
	v_mfma_f32_16x16x32_bf16 v[76:79], v[36:39], v[52:55], v[76:79]
	v_mfma_f32_16x16x32_bf16 v[80:83], v[36:39], v[56:59], v[80:83]
	v_mfma_f32_16x16x32_bf16 v[84:87], v[40:43], v[52:55], v[84:87]
	v_mfma_f32_16x16x32_bf16 v[88:91], v[40:43], v[56:59], v[88:91]
	s_nop 3
	global_load_dwordx4 v[124:127], v249, s[16:17] offset:0
	global_load_dwordx4 v[128:131], v249, s[16:17] offset:64
	global_load_dwordx4 v[132:135], v249, s[16:17] offset:128
	global_load_dwordx4 v[136:139], v249, s[16:17] offset:192
	s_cmp_lt_u32 s33, 28
	s_cselect_b32 s43, 0x200, 0
	s_add_u32 s16, s16, s43
	s_addc_u32 s17, s17, 0
	s_add_i32 s33, s33, 1
	s_nop 7
	s_nop 7
	v_cvt_pk_bf16_f32 v140, v60, v61
	v_cvt_pk_bf16_f32 v141, v62, v63
	ds_write_b64 v215, v[140:141] offset:12544
	v_cvt_pk_bf16_f32 v144, v64, v65
	v_cvt_pk_bf16_f32 v145, v66, v67
	ds_write_b64 v215, v[144:145] offset:16640
	s_nop 1
	v_cvt_pk_bf16_f32 v140, v68, v69
	v_cvt_pk_bf16_f32 v141, v70, v71
	ds_write_b64 v214, v[140:141] offset:12544
	v_cvt_pk_bf16_f32 v144, v72, v73
	v_cvt_pk_bf16_f32 v145, v74, v75
	ds_write_b64 v214, v[144:145] offset:16640
	s_nop 1
	v_cvt_pk_bf16_f32 v140, v76, v77
	v_cvt_pk_bf16_f32 v141, v78, v79
	ds_write_b64 v213, v[140:141] offset:12544
	v_cvt_pk_bf16_f32 v144, v80, v81
	v_cvt_pk_bf16_f32 v145, v82, v83
	ds_write_b64 v213, v[144:145] offset:16640
	s_nop 1
	v_cvt_pk_bf16_f32 v140, v84, v85
	v_cvt_pk_bf16_f32 v141, v86, v87
	ds_write_b64 v212, v[140:141] offset:12544
	v_cvt_pk_bf16_f32 v144, v88, v89
	v_cvt_pk_bf16_f32 v145, v90, v91
	ds_write_b64 v212, v[144:145] offset:16640
	s_nop 1
	s_waitcnt vmcnt(13)
	s_waitcnt lgkmcnt(0)
	s_barrier
	ds_read_b128 v[44:47], v217 offset:12288
	ds_read_b128 v[48:51], v217 offset:14336
	ds_read_b128 v[12:15], v227 offset:0
	ds_read_b128 v[16:19], v227 offset:2048
	ds_read_b128 v[20:23], v227 offset:4096
	ds_read_b128 v[24:27], v227 offset:6144
	ds_read_b128 v[52:55], v216 offset:12288
	ds_read_b128 v[56:59], v216 offset:14336
	ds_read_b128 v[28:31], v226 offset:0
	ds_read_b128 v[32:35], v226 offset:2048
	ds_read_b128 v[36:39], v226 offset:4096
	ds_read_b128 v[40:43], v226 offset:6144
	s_waitcnt vmcnt(18)
	v_pk_mul_f32 v[60:61], v[60:61], v[92:93]
	v_pk_mul_f32 v[62:63], v[62:63], v[94:95]
	v_pk_mul_f32 v[64:65], v[64:65], v[92:93]
	v_pk_mul_f32 v[66:67], v[66:67], v[94:95]
	v_pk_mul_f32 v[68:69], v[68:69], v[96:97]
	v_pk_mul_f32 v[70:71], v[70:71], v[98:99]
	v_pk_mul_f32 v[72:73], v[72:73], v[96:97]
	v_pk_mul_f32 v[74:75], v[74:75], v[98:99]
	v_pk_mul_f32 v[76:77], v[76:77], v[100:101]
	v_pk_mul_f32 v[78:79], v[78:79], v[102:103]
	v_pk_mul_f32 v[80:81], v[80:81], v[100:101]
	v_pk_mul_f32 v[82:83], v[82:83], v[102:103]
	v_pk_mul_f32 v[84:85], v[84:85], v[104:105]
	v_pk_mul_f32 v[86:87], v[86:87], v[106:107]
	v_pk_mul_f32 v[88:89], v[88:89], v[104:105]
	v_pk_mul_f32 v[90:91], v[90:91], v[106:107]
	s_add_i32 m0, s46, 0x14000
	s_nop 0
	global_load_lds_dwordx4 v255, s[8:9]
	s_add_i32 m0, s46, 0x14400
	s_nop 0
	global_load_lds_dwordx4 v254, s[8:9]
	s_add_i32 m0, s47, 0x14000
	s_nop 0
	global_load_lds_dwordx4 v253, s[10:11]
	s_add_i32 m0, s48, 0x14000
	s_nop 0
	global_load_lds_dwordx4 v252, s[12:13]
	s_add_i32 m0, s48, 0x14400
	s_nop 0
	global_load_lds_dwordx4 v251, s[12:13]
	s_cmp_lt_u32 s33, 29
	s_cselect_b32 s43, 0x10000, 0
	s_add_u32 s8, s8, s43
	s_addc_u32 s9, s9, 0
	s_cmp_lt_u32 s33, 29
	s_cselect_b32 s43, 0x2000, 0
	s_add_u32 s10, s10, s43
	s_addc_u32 s11, s11, 0
	s_cmp_lt_u32 s33, 29
	s_cselect_b32 s43, 0x4000, 0
	s_add_u32 s12, s12, s43
	s_addc_u32 s13, s13, 0
	s_waitcnt lgkmcnt(6)
	v_mfma_f32_16x16x32_bf16 v[60:63], v[12:15], v[44:47], v[60:63]
	v_mfma_f32_16x16x32_bf16 v[64:67], v[12:15], v[48:51], v[64:67]
	v_mfma_f32_16x16x32_bf16 v[68:71], v[16:19], v[44:47], v[68:71]
	v_mfma_f32_16x16x32_bf16 v[72:75], v[16:19], v[48:51], v[72:75]
	v_mfma_f32_16x16x32_bf16 v[76:79], v[20:23], v[44:47], v[76:79]
	v_mfma_f32_16x16x32_bf16 v[80:83], v[20:23], v[48:51], v[80:83]
	v_mfma_f32_16x16x32_bf16 v[84:87], v[24:27], v[44:47], v[84:87]
	v_mfma_f32_16x16x32_bf16 v[88:91], v[24:27], v[48:51], v[88:91]
	s_waitcnt lgkmcnt(0)
	v_mfma_f32_16x16x32_bf16 v[60:63], v[28:31], v[52:55], v[60:63]
	v_mfma_f32_16x16x32_bf16 v[64:67], v[28:31], v[56:59], v[64:67]
	v_mfma_f32_16x16x32_bf16 v[68:71], v[32:35], v[52:55], v[68:71]
	v_mfma_f32_16x16x32_bf16 v[72:75], v[32:35], v[56:59], v[72:75]
	v_mfma_f32_16x16x32_bf16 v[76:79], v[36:39], v[52:55], v[76:79]
	v_mfma_f32_16x16x32_bf16 v[80:83], v[36:39], v[56:59], v[80:83]
	v_mfma_f32_16x16x32_bf16 v[84:87], v[40:43], v[52:55], v[84:87]
	v_mfma_f32_16x16x32_bf16 v[88:91], v[40:43], v[56:59], v[88:91]
	s_nop 3
	global_load_dwordx4 v[92:95], v249, s[16:17] offset:0
	global_load_dwordx4 v[96:99], v249, s[16:17] offset:64
	global_load_dwordx4 v[100:103], v249, s[16:17] offset:128
	global_load_dwordx4 v[104:107], v249, s[16:17] offset:192
	s_cmp_lt_u32 s33, 28
	s_cselect_b32 s43, 0x200, 0
	s_add_u32 s16, s16, s43
	s_addc_u32 s17, s17, 0
	s_add_i32 s33, s33, 1
	s_nop 7
	s_nop 7
	v_cvt_pk_bf16_f32 v140, v60, v61
	v_cvt_pk_bf16_f32 v141, v62, v63
	ds_write_b64 v215, v[140:141] offset:0
	v_cvt_pk_bf16_f32 v144, v64, v65
	v_cvt_pk_bf16_f32 v145, v66, v67
	ds_write_b64 v215, v[144:145] offset:4096
	s_nop 1
	v_cvt_pk_bf16_f32 v140, v68, v69
	v_cvt_pk_bf16_f32 v141, v70, v71
	ds_write_b64 v214, v[140:141] offset:0
	v_cvt_pk_bf16_f32 v144, v72, v73
	v_cvt_pk_bf16_f32 v145, v74, v75
	ds_write_b64 v214, v[144:145] offset:4096
	s_nop 1
	v_cvt_pk_bf16_f32 v140, v76, v77
	v_cvt_pk_bf16_f32 v141, v78, v79
	ds_write_b64 v213, v[140:141] offset:0
	v_cvt_pk_bf16_f32 v144, v80, v81
	v_cvt_pk_bf16_f32 v145, v82, v83
	ds_write_b64 v213, v[144:145] offset:4096
	s_nop 1
	v_cvt_pk_bf16_f32 v140, v84, v85
	v_cvt_pk_bf16_f32 v141, v86, v87
	ds_write_b64 v212, v[140:141] offset:0
	v_cvt_pk_bf16_f32 v144, v88, v89
	v_cvt_pk_bf16_f32 v145, v90, v91
	ds_write_b64 v212, v[144:145] offset:4096
	s_nop 1
	s_waitcnt vmcnt(13)
	s_waitcnt lgkmcnt(0)
	s_barrier
	ds_read_b128 v[44:47], v217 offset:0
	ds_read_b128 v[48:51], v217 offset:2048
	ds_read_b128 v[12:15], v227 offset:40960
	ds_read_b128 v[16:19], v227 offset:43008
	ds_read_b128 v[20:23], v227 offset:45056
	ds_read_b128 v[24:27], v227 offset:47104
	ds_read_b128 v[52:55], v216 offset:0
	ds_read_b128 v[56:59], v216 offset:2048
	ds_read_b128 v[28:31], v226 offset:40960
	ds_read_b128 v[32:35], v226 offset:43008
	ds_read_b128 v[36:39], v226 offset:45056
	ds_read_b128 v[40:43], v226 offset:47104
	s_waitcnt vmcnt(18)
	v_pk_mul_f32 v[60:61], v[60:61], v[108:109]
	v_pk_mul_f32 v[62:63], v[62:63], v[110:111]
	v_pk_mul_f32 v[64:65], v[64:65], v[108:109]
	v_pk_mul_f32 v[66:67], v[66:67], v[110:111]
	v_pk_mul_f32 v[68:69], v[68:69], v[112:113]
	v_pk_mul_f32 v[70:71], v[70:71], v[114:115]
	v_pk_mul_f32 v[72:73], v[72:73], v[112:113]
	v_pk_mul_f32 v[74:75], v[74:75], v[114:115]
	v_pk_mul_f32 v[76:77], v[76:77], v[116:117]
	v_pk_mul_f32 v[78:79], v[78:79], v[118:119]
	v_pk_mul_f32 v[80:81], v[80:81], v[116:117]
	v_pk_mul_f32 v[82:83], v[82:83], v[118:119]
	v_pk_mul_f32 v[84:85], v[84:85], v[120:121]
	v_pk_mul_f32 v[86:87], v[86:87], v[122:123]
	v_pk_mul_f32 v[88:89], v[88:89], v[120:121]
	v_pk_mul_f32 v[90:91], v[90:91], v[122:123]
	s_mov_b32 m0, s46
	s_nop 0
	global_load_lds_dwordx4 v255, s[8:9]
	s_add_i32 m0, s46, 0x400
	s_nop 0
	global_load_lds_dwordx4 v254, s[8:9]
	s_mov_b32 m0, s47
	s_nop 0
	global_load_lds_dwordx4 v253, s[10:11]
	s_mov_b32 m0, s48
	s_nop 0
	global_load_lds_dwordx4 v252, s[12:13]
	s_add_i32 m0, s48, 0x400
	s_nop 0
	global_load_lds_dwordx4 v251, s[12:13]
	s_cmp_lt_u32 s33, 29
	s_cselect_b32 s43, 0x10000, 0
	s_add_u32 s8, s8, s43
	s_addc_u32 s9, s9, 0
	s_cmp_lt_u32 s33, 29
	s_cselect_b32 s43, 0x2000, 0
	s_add_u32 s10, s10, s43
	s_addc_u32 s11, s11, 0
	s_cmp_lt_u32 s33, 29
	s_cselect_b32 s43, 0x4000, 0
	s_add_u32 s12, s12, s43
	s_addc_u32 s13, s13, 0
	s_waitcnt lgkmcnt(6)
	v_mfma_f32_16x16x32_bf16 v[60:63], v[12:15], v[44:47], v[60:63]
	v_mfma_f32_16x16x32_bf16 v[64:67], v[12:15], v[48:51], v[64:67]
	v_mfma_f32_16x16x32_bf16 v[68:71], v[16:19], v[44:47], v[68:71]
	v_mfma_f32_16x16x32_bf16 v[72:75], v[16:19], v[48:51], v[72:75]
	v_mfma_f32_16x16x32_bf16 v[76:79], v[20:23], v[44:47], v[76:79]
	v_mfma_f32_16x16x32_bf16 v[80:83], v[20:23], v[48:51], v[80:83]
	v_mfma_f32_16x16x32_bf16 v[84:87], v[24:27], v[44:47], v[84:87]
	v_mfma_f32_16x16x32_bf16 v[88:91], v[24:27], v[48:51], v[88:91]
	s_waitcnt lgkmcnt(0)
	v_mfma_f32_16x16x32_bf16 v[60:63], v[28:31], v[52:55], v[60:63]
	v_mfma_f32_16x16x32_bf16 v[64:67], v[28:31], v[56:59], v[64:67]
	v_mfma_f32_16x16x32_bf16 v[68:71], v[32:35], v[52:55], v[68:71]
	v_mfma_f32_16x16x32_bf16 v[72:75], v[32:35], v[56:59], v[72:75]
	v_mfma_f32_16x16x32_bf16 v[76:79], v[36:39], v[52:55], v[76:79]
	v_mfma_f32_16x16x32_bf16 v[80:83], v[36:39], v[56:59], v[80:83]
	v_mfma_f32_16x16x32_bf16 v[84:87], v[40:43], v[52:55], v[84:87]
	v_mfma_f32_16x16x32_bf16 v[88:91], v[40:43], v[56:59], v[88:91]
	s_nop 3
	global_load_dwordx4 v[108:111], v249, s[16:17] offset:0
	global_load_dwordx4 v[112:115], v249, s[16:17] offset:64
	global_load_dwordx4 v[116:119], v249, s[16:17] offset:128
	global_load_dwordx4 v[120:123], v249, s[16:17] offset:192
	s_cmp_lt_u32 s33, 28
	s_cselect_b32 s43, 0x200, 0
	s_add_u32 s16, s16, s43
	s_addc_u32 s17, s17, 0
	s_add_i32 s33, s33, 1
	s_nop 7
	s_nop 7
	v_cvt_pk_bf16_f32 v140, v60, v61
	v_cvt_pk_bf16_f32 v141, v62, v63
	ds_write_b64 v215, v[140:141] offset:12544
	v_cvt_pk_bf16_f32 v144, v64, v65
	v_cvt_pk_bf16_f32 v145, v66, v67
	ds_write_b64 v215, v[144:145] offset:16640
	s_nop 1
	v_cvt_pk_bf16_f32 v140, v68, v69
	v_cvt_pk_bf16_f32 v141, v70, v71
	ds_write_b64 v214, v[140:141] offset:12544
	v_cvt_pk_bf16_f32 v144, v72, v73
	v_cvt_pk_bf16_f32 v145, v74, v75
	ds_write_b64 v214, v[144:145] offset:16640
	s_nop 1
	v_cvt_pk_bf16_f32 v140, v76, v77
	v_cvt_pk_bf16_f32 v141, v78, v79
	ds_write_b64 v213, v[140:141] offset:12544
	v_cvt_pk_bf16_f32 v144, v80, v81
	v_cvt_pk_bf16_f32 v145, v82, v83
	ds_write_b64 v213, v[144:145] offset:16640
	s_nop 1
	v_cvt_pk_bf16_f32 v140, v84, v85
	v_cvt_pk_bf16_f32 v141, v86, v87
	ds_write_b64 v212, v[140:141] offset:12544
	v_cvt_pk_bf16_f32 v144, v88, v89
	v_cvt_pk_bf16_f32 v145, v90, v91
	ds_write_b64 v212, v[144:145] offset:16640
	s_nop 1
	s_waitcnt vmcnt(13)
	s_waitcnt lgkmcnt(0)
	s_barrier
	ds_read_b128 v[44:47], v217 offset:12288
	ds_read_b128 v[48:51], v217 offset:14336
	ds_read_b128 v[12:15], v225 offset:0
	ds_read_b128 v[16:19], v225 offset:2048
	ds_read_b128 v[20:23], v225 offset:4096
	ds_read_b128 v[24:27], v225 offset:6144
	ds_read_b128 v[52:55], v216 offset:12288
	ds_read_b128 v[56:59], v216 offset:14336
	ds_read_b128 v[28:31], v224 offset:0
	ds_read_b128 v[32:35], v224 offset:2048
	ds_read_b128 v[36:39], v224 offset:4096
	ds_read_b128 v[40:43], v224 offset:6144
	s_waitcnt vmcnt(18)
	v_pk_mul_f32 v[60:61], v[60:61], v[124:125]
	v_pk_mul_f32 v[62:63], v[62:63], v[126:127]
	v_pk_mul_f32 v[64:65], v[64:65], v[124:125]
	v_pk_mul_f32 v[66:67], v[66:67], v[126:127]
	v_pk_mul_f32 v[68:69], v[68:69], v[128:129]
	v_pk_mul_f32 v[70:71], v[70:71], v[130:131]
	v_pk_mul_f32 v[72:73], v[72:73], v[128:129]
	v_pk_mul_f32 v[74:75], v[74:75], v[130:131]
	v_pk_mul_f32 v[76:77], v[76:77], v[132:133]
	v_pk_mul_f32 v[78:79], v[78:79], v[134:135]
	v_pk_mul_f32 v[80:81], v[80:81], v[132:133]
	v_pk_mul_f32 v[82:83], v[82:83], v[134:135]
	v_pk_mul_f32 v[84:85], v[84:85], v[136:137]
	v_pk_mul_f32 v[86:87], v[86:87], v[138:139]
	v_pk_mul_f32 v[88:89], v[88:89], v[136:137]
	v_pk_mul_f32 v[90:91], v[90:91], v[138:139]
	s_add_i32 m0, s46, 0xa000
	s_nop 0
	global_load_lds_dwordx4 v255, s[8:9]
	s_add_i32 m0, s46, 0xa400
	s_nop 0
	global_load_lds_dwordx4 v254, s[8:9]
	s_add_i32 m0, s47, 0xa000
	s_nop 0
	global_load_lds_dwordx4 v253, s[10:11]
	s_add_i32 m0, s48, 0xa000
	s_nop 0
	global_load_lds_dwordx4 v252, s[12:13]
	s_add_i32 m0, s48, 0xa400
	s_nop 0
	global_load_lds_dwordx4 v251, s[12:13]
	s_cmp_lt_u32 s33, 29
	s_cselect_b32 s43, 0x10000, 0
	s_add_u32 s8, s8, s43
	s_addc_u32 s9, s9, 0
	s_cmp_lt_u32 s33, 29
	s_cselect_b32 s43, 0x2000, 0
	s_add_u32 s10, s10, s43
	s_addc_u32 s11, s11, 0
	s_cmp_lt_u32 s33, 29
	s_cselect_b32 s43, 0x4000, 0
	s_add_u32 s12, s12, s43
	s_addc_u32 s13, s13, 0
	s_waitcnt lgkmcnt(6)
	v_mfma_f32_16x16x32_bf16 v[60:63], v[12:15], v[44:47], v[60:63]
	v_mfma_f32_16x16x32_bf16 v[64:67], v[12:15], v[48:51], v[64:67]
	v_mfma_f32_16x16x32_bf16 v[68:71], v[16:19], v[44:47], v[68:71]
	v_mfma_f32_16x16x32_bf16 v[72:75], v[16:19], v[48:51], v[72:75]
	v_mfma_f32_16x16x32_bf16 v[76:79], v[20:23], v[44:47], v[76:79]
	v_mfma_f32_16x16x32_bf16 v[80:83], v[20:23], v[48:51], v[80:83]
	v_mfma_f32_16x16x32_bf16 v[84:87], v[24:27], v[44:47], v[84:87]
	v_mfma_f32_16x16x32_bf16 v[88:91], v[24:27], v[48:51], v[88:91]
	s_waitcnt lgkmcnt(0)
	v_mfma_f32_16x16x32_bf16 v[60:63], v[28:31], v[52:55], v[60:63]
	v_mfma_f32_16x16x32_bf16 v[64:67], v[28:31], v[56:59], v[64:67]
	v_mfma_f32_16x16x32_bf16 v[68:71], v[32:35], v[52:55], v[68:71]
	v_mfma_f32_16x16x32_bf16 v[72:75], v[32:35], v[56:59], v[72:75]
	v_mfma_f32_16x16x32_bf16 v[76:79], v[36:39], v[52:55], v[76:79]
	v_mfma_f32_16x16x32_bf16 v[80:83], v[36:39], v[56:59], v[80:83]
	v_mfma_f32_16x16x32_bf16 v[84:87], v[40:43], v[52:55], v[84:87]
	v_mfma_f32_16x16x32_bf16 v[88:91], v[40:43], v[56:59], v[88:91]
	s_nop 3
	global_load_dwordx4 v[124:127], v249, s[16:17] offset:0
	global_load_dwordx4 v[128:131], v249, s[16:17] offset:64
	global_load_dwordx4 v[132:135], v249, s[16:17] offset:128
	global_load_dwordx4 v[136:139], v249, s[16:17] offset:192
	s_cmp_lt_u32 s33, 28
	s_cselect_b32 s43, 0x200, 0
	s_add_u32 s16, s16, s43
	s_addc_u32 s17, s17, 0
	s_add_i32 s33, s33, 1
	s_nop 7
	s_nop 7
	v_cvt_pk_bf16_f32 v140, v60, v61
	v_cvt_pk_bf16_f32 v141, v62, v63
	ds_write_b64 v215, v[140:141] offset:0
	v_cvt_pk_bf16_f32 v144, v64, v65
	v_cvt_pk_bf16_f32 v145, v66, v67
	ds_write_b64 v215, v[144:145] offset:4096
	s_nop 1
	v_cvt_pk_bf16_f32 v140, v68, v69
	v_cvt_pk_bf16_f32 v141, v70, v71
	ds_write_b64 v214, v[140:141] offset:0
	v_cvt_pk_bf16_f32 v144, v72, v73
	v_cvt_pk_bf16_f32 v145, v74, v75
	ds_write_b64 v214, v[144:145] offset:4096
	s_nop 1
	v_cvt_pk_bf16_f32 v140, v76, v77
	v_cvt_pk_bf16_f32 v141, v78, v79
	ds_write_b64 v213, v[140:141] offset:0
	v_cvt_pk_bf16_f32 v144, v80, v81
	v_cvt_pk_bf16_f32 v145, v82, v83
	ds_write_b64 v213, v[144:145] offset:4096
	s_nop 1
	v_cvt_pk_bf16_f32 v140, v84, v85
	v_cvt_pk_bf16_f32 v141, v86, v87
	ds_write_b64 v212, v[140:141] offset:0
	v_cvt_pk_bf16_f32 v144, v88, v89
	v_cvt_pk_bf16_f32 v145, v90, v91
	ds_write_b64 v212, v[144:145] offset:4096
	s_nop 1
	s_waitcnt vmcnt(13)
	s_waitcnt lgkmcnt(0)
	s_barrier
	s_cmp_lt_u32 s33, 30
	s_cbranch_scc1 .Lp3S_loop
	ds_read_b128 v[44:47], v217 offset:0
	ds_read_b128 v[48:51], v217 offset:2048
	ds_read_b128 v[12:15], v227 offset:0
	ds_read_b128 v[16:19], v227 offset:2048
	ds_read_b128 v[20:23], v227 offset:4096
	ds_read_b128 v[24:27], v227 offset:6144
	ds_read_b128 v[52:55], v216 offset:0
	ds_read_b128 v[56:59], v216 offset:2048
	ds_read_b128 v[28:31], v226 offset:0
	ds_read_b128 v[32:35], v226 offset:2048
	ds_read_b128 v[36:39], v226 offset:4096
	ds_read_b128 v[40:43], v226 offset:6144
	s_waitcnt vmcnt(18)
	v_pk_mul_f32 v[60:61], v[60:61], v[92:93]
	v_pk_mul_f32 v[62:63], v[62:63], v[94:95]
	v_pk_mul_f32 v[64:65], v[64:65], v[92:93]
	v_pk_mul_f32 v[66:67], v[66:67], v[94:95]
	v_pk_mul_f32 v[68:69], v[68:69], v[96:97]
	v_pk_mul_f32 v[70:71], v[70:71], v[98:99]
	v_pk_mul_f32 v[72:73], v[72:73], v[96:97]
	v_pk_mul_f32 v[74:75], v[74:75], v[98:99]
	v_pk_mul_f32 v[76:77], v[76:77], v[100:101]
	v_pk_mul_f32 v[78:79], v[78:79], v[102:103]
	v_pk_mul_f32 v[80:81], v[80:81], v[100:101]
	v_pk_mul_f32 v[82:83], v[82:83], v[102:103]
	v_pk_mul_f32 v[84:85], v[84:85], v[104:105]
	v_pk_mul_f32 v[86:87], v[86:87], v[106:107]
	v_pk_mul_f32 v[88:89], v[88:89], v[104:105]
	v_pk_mul_f32 v[90:91], v[90:91], v[106:107]
	s_add_i32 m0, s46, 0x14000
	s_nop 0
	global_load_lds_dwordx4 v255, s[8:9]
	s_add_i32 m0, s46, 0x14400
	s_nop 0
	global_load_lds_dwordx4 v254, s[8:9]
	s_add_i32 m0, s47, 0x14000
	s_nop 0
	global_load_lds_dwordx4 v253, s[10:11]
	s_add_i32 m0, s48, 0x14000
	s_nop 0
	global_load_lds_dwordx4 v252, s[12:13]
	s_add_i32 m0, s48, 0x14400
	s_nop 0
	global_load_lds_dwordx4 v251, s[12:13]
	s_cmp_lt_u32 s33, 29
	s_cselect_b32 s43, 0x10000, 0
	s_add_u32 s8, s8, s43
	s_addc_u32 s9, s9, 0
	s_cmp_lt_u32 s33, 29
	s_cselect_b32 s43, 0x2000, 0
	s_add_u32 s10, s10, s43
	s_addc_u32 s11, s11, 0
	s_cmp_lt_u32 s33, 29
	s_cselect_b32 s43, 0x4000, 0
	s_add_u32 s12, s12, s43
	s_addc_u32 s13, s13, 0
	s_waitcnt lgkmcnt(6)
	v_mfma_f32_16x16x32_bf16 v[60:63], v[12:15], v[44:47], v[60:63]
	v_mfma_f32_16x16x32_bf16 v[64:67], v[12:15], v[48:51], v[64:67]
	v_mfma_f32_16x16x32_bf16 v[68:71], v[16:19], v[44:47], v[68:71]
	v_mfma_f32_16x16x32_bf16 v[72:75], v[16:19], v[48:51], v[72:75]
	v_mfma_f32_16x16x32_bf16 v[76:79], v[20:23], v[44:47], v[76:79]
	v_mfma_f32_16x16x32_bf16 v[80:83], v[20:23], v[48:51], v[80:83]
	v_mfma_f32_16x16x32_bf16 v[84:87], v[24:27], v[44:47], v[84:87]
	v_mfma_f32_16x16x32_bf16 v[88:91], v[24:27], v[48:51], v[88:91]
	s_waitcnt lgkmcnt(0)
	v_mfma_f32_16x16x32_bf16 v[60:63], v[28:31], v[52:55], v[60:63]
	v_mfma_f32_16x16x32_bf16 v[64:67], v[28:31], v[56:59], v[64:67]
	v_mfma_f32_16x16x32_bf16 v[68:71], v[32:35], v[52:55], v[68:71]
	v_mfma_f32_16x16x32_bf16 v[72:75], v[32:35], v[56:59], v[72:75]
	v_mfma_f32_16x16x32_bf16 v[76:79], v[36:39], v[52:55], v[76:79]
	v_mfma_f32_16x16x32_bf16 v[80:83], v[36:39], v[56:59], v[80:83]
	v_mfma_f32_16x16x32_bf16 v[84:87], v[40:43], v[52:55], v[84:87]
	v_mfma_f32_16x16x32_bf16 v[88:91], v[40:43], v[56:59], v[88:91]
	s_nop 3
	global_load_dwordx4 v[92:95], v249, s[16:17] offset:0
	global_load_dwordx4 v[96:99], v249, s[16:17] offset:64
	global_load_dwordx4 v[100:103], v249, s[16:17] offset:128
	global_load_dwordx4 v[104:107], v249, s[16:17] offset:192
	s_cmp_lt_u32 s33, 28
	s_cselect_b32 s43, 0x200, 0
	s_add_u32 s16, s16, s43
	s_addc_u32 s17, s17, 0
	s_add_i32 s33, s33, 1
	s_nop 7
	s_nop 7
	v_cvt_pk_bf16_f32 v140, v60, v61
	v_cvt_pk_bf16_f32 v141, v62, v63
	ds_write_b64 v215, v[140:141] offset:12544
	v_cvt_pk_bf16_f32 v144, v64, v65
	v_cvt_pk_bf16_f32 v145, v66, v67
	ds_write_b64 v215, v[144:145] offset:16640
	s_nop 1
	v_cvt_pk_bf16_f32 v140, v68, v69
	v_cvt_pk_bf16_f32 v141, v70, v71
	ds_write_b64 v214, v[140:141] offset:12544
	v_cvt_pk_bf16_f32 v144, v72, v73
	v_cvt_pk_bf16_f32 v145, v74, v75
	ds_write_b64 v214, v[144:145] offset:16640
	s_nop 1
	v_cvt_pk_bf16_f32 v140, v76, v77
	v_cvt_pk_bf16_f32 v141, v78, v79
	ds_write_b64 v213, v[140:141] offset:12544
	v_cvt_pk_bf16_f32 v144, v80, v81
	v_cvt_pk_bf16_f32 v145, v82, v83
	ds_write_b64 v213, v[144:145] offset:16640
	s_nop 1
	v_cvt_pk_bf16_f32 v140, v84, v85
	v_cvt_pk_bf16_f32 v141, v86, v87
	ds_write_b64 v212, v[140:141] offset:12544
	v_cvt_pk_bf16_f32 v144, v88, v89
	v_cvt_pk_bf16_f32 v145, v90, v91
	ds_write_b64 v212, v[144:145] offset:16640
	s_nop 1
	s_waitcnt vmcnt(13)
	s_waitcnt lgkmcnt(0)
	s_barrier
; __device__ __forceinline__ void gla_scan_item(const Ctx& C, int item, LAS unsigned char* lds, int tid) {
;     ...
;     SCAN_LOAD(A, 0); SCAN_LOAD(B, 1);
; #pragma unroll
;     for (int n = 0; n < 32; n += 2) { SCAN_STEP(A, n); SCAN_STEP(B, n + 1); }
;     ...
;     float* So = C.out + OUT_GLAP + ((size_t)bh * 128 + wave * 16 + quad * 4) * 256 + sl * 32 + l15;
; #pragma unroll
;     for (int v2 = 0; v2 < 2; ++v2)
; #pragma unroll
;         for (int j = 0; j < 4; ++j) So[(size_t)j * 256 + v2 * 16] = S[v2][j];
	ds_read_b128 v[44:47], v217 offset:12288
	ds_read_b128 v[48:51], v217 offset:14336
	ds_read_b128 v[12:15], v227 offset:40960
	ds_read_b128 v[16:19], v227 offset:43008
	ds_read_b128 v[20:23], v227 offset:45056
	ds_read_b128 v[24:27], v227 offset:47104
	ds_read_b128 v[52:55], v216 offset:12288
	ds_read_b128 v[56:59], v216 offset:14336
	ds_read_b128 v[28:31], v226 offset:40960
	ds_read_b128 v[32:35], v226 offset:43008
	ds_read_b128 v[36:39], v226 offset:45056
	ds_read_b128 v[40:43], v226 offset:47104
	s_waitcnt vmcnt(18)
	v_pk_mul_f32 v[60:61], v[60:61], v[108:109]
	v_pk_mul_f32 v[62:63], v[62:63], v[110:111]
	v_pk_mul_f32 v[64:65], v[64:65], v[108:109]
	v_pk_mul_f32 v[66:67], v[66:67], v[110:111]
	v_pk_mul_f32 v[68:69], v[68:69], v[112:113]
	v_pk_mul_f32 v[70:71], v[70:71], v[114:115]
	v_pk_mul_f32 v[72:73], v[72:73], v[112:113]
	v_pk_mul_f32 v[74:75], v[74:75], v[114:115]
	v_pk_mul_f32 v[76:77], v[76:77], v[116:117]
	v_pk_mul_f32 v[78:79], v[78:79], v[118:119]
	v_pk_mul_f32 v[80:81], v[80:81], v[116:117]
	v_pk_mul_f32 v[82:83], v[82:83], v[118:119]
	v_pk_mul_f32 v[84:85], v[84:85], v[120:121]
	v_pk_mul_f32 v[86:87], v[86:87], v[122:123]
	v_pk_mul_f32 v[88:89], v[88:89], v[120:121]
	v_pk_mul_f32 v[90:91], v[90:91], v[122:123]
	s_mov_b32 m0, s46
	s_nop 0
	global_load_lds_dwordx4 v255, s[8:9]
	s_add_i32 m0, s46, 0x400
	s_nop 0
	global_load_lds_dwordx4 v254, s[8:9]
	s_mov_b32 m0, s47
	s_nop 0
	global_load_lds_dwordx4 v253, s[10:11]
	s_mov_b32 m0, s48
	s_nop 0
	global_load_lds_dwordx4 v252, s[12:13]
	s_add_i32 m0, s48, 0x400
	s_nop 0
	global_load_lds_dwordx4 v251, s[12:13]
	s_cmp_lt_u32 s33, 29
	s_cselect_b32 s43, 0x10000, 0
	s_add_u32 s8, s8, s43
	s_addc_u32 s9, s9, 0
	s_cmp_lt_u32 s33, 29
	s_cselect_b32 s43, 0x2000, 0
	s_add_u32 s10, s10, s43
	s_addc_u32 s11, s11, 0
	s_cmp_lt_u32 s33, 29
	s_cselect_b32 s43, 0x4000, 0
	s_add_u32 s12, s12, s43
	s_addc_u32 s13, s13, 0
	s_waitcnt lgkmcnt(6)
	v_mfma_f32_16x16x32_bf16 v[60:63], v[12:15], v[44:47], v[60:63]
	v_mfma_f32_16x16x32_bf16 v[64:67], v[12:15], v[48:51], v[64:67]
	v_mfma_f32_16x16x32_bf16 v[68:71], v[16:19], v[44:47], v[68:71]
	v_mfma_f32_16x16x32_bf16 v[72:75], v[16:19], v[48:51], v[72:75]
	v_mfma_f32_16x16x32_bf16 v[76:79], v[20:23], v[44:47], v[76:79]
	v_mfma_f32_16x16x32_bf16 v[80:83], v[20:23], v[48:51], v[80:83]
	v_mfma_f32_16x16x32_bf16 v[84:87], v[24:27], v[44:47], v[84:87]
	v_mfma_f32_16x16x32_bf16 v[88:91], v[24:27], v[48:51], v[88:91]
	s_waitcnt lgkmcnt(0)
	v_mfma_f32_16x16x32_bf16 v[60:63], v[28:31], v[52:55], v[60:63]
	v_mfma_f32_16x16x32_bf16 v[64:67], v[28:31], v[56:59], v[64:67]
	v_mfma_f32_16x16x32_bf16 v[68:71], v[32:35], v[52:55], v[68:71]
	v_mfma_f32_16x16x32_bf16 v[72:75], v[32:35], v[56:59], v[72:75]
	v_mfma_f32_16x16x32_bf16 v[76:79], v[36:39], v[52:55], v[76:79]
	v_mfma_f32_16x16x32_bf16 v[80:83], v[36:39], v[56:59], v[80:83]
	v_mfma_f32_16x16x32_bf16 v[84:87], v[40:43], v[52:55], v[84:87]
	v_mfma_f32_16x16x32_bf16 v[88:91], v[40:43], v[56:59], v[88:91]
	s_nop 3
	global_load_dwordx4 v[108:111], v249, s[16:17] offset:0
	global_load_dwordx4 v[112:115], v249, s[16:17] offset:64
	global_load_dwordx4 v[116:119], v249, s[16:17] offset:128
	global_load_dwordx4 v[120:123], v249, s[16:17] offset:192
	s_cmp_lt_u32 s33, 28
	s_cselect_b32 s43, 0x200, 0
	s_add_u32 s16, s16, s43
	s_addc_u32 s17, s17, 0
	s_add_i32 s33, s33, 1
	s_nop 7
	s_nop 7
	v_cvt_pk_bf16_f32 v140, v60, v61
	v_cvt_pk_bf16_f32 v141, v62, v63
	ds_write_b64 v215, v[140:141] offset:0
	v_cvt_pk_bf16_f32 v144, v64, v65
	v_cvt_pk_bf16_f32 v145, v66, v67
	ds_write_b64 v215, v[144:145] offset:4096
	s_nop 1
	v_cvt_pk_bf16_f32 v140, v68, v69
	v_cvt_pk_bf16_f32 v141, v70, v71
	ds_write_b64 v214, v[140:141] offset:0
	v_cvt_pk_bf16_f32 v144, v72, v73
	v_cvt_pk_bf16_f32 v145, v74, v75
	ds_write_b64 v214, v[144:145] offset:4096
	s_nop 1
	v_cvt_pk_bf16_f32 v140, v76, v77
	v_cvt_pk_bf16_f32 v141, v78, v79
	ds_write_b64 v213, v[140:141] offset:0
	v_cvt_pk_bf16_f32 v144, v80, v81
	v_cvt_pk_bf16_f32 v145, v82, v83
	ds_write_b64 v213, v[144:145] offset:4096
	s_nop 1
	v_cvt_pk_bf16_f32 v140, v84, v85
	v_cvt_pk_bf16_f32 v141, v86, v87
	ds_write_b64 v212, v[140:141] offset:0
	v_cvt_pk_bf16_f32 v144, v88, v89
	v_cvt_pk_bf16_f32 v145, v90, v91
	ds_write_b64 v212, v[144:145] offset:4096
	s_nop 1
	s_waitcnt vmcnt(13)
	s_waitcnt lgkmcnt(0)
	s_barrier
	s_nop 7
	global_store_dword v245, v60, s[34:35] offset:0
	global_store_dword v245, v61, s[34:35] offset:1024
	global_store_dword v245, v62, s[34:35] offset:2048
	global_store_dword v245, v63, s[34:35] offset:3072
	global_store_dword v245, v64, s[34:35] offset:64
	global_store_dword v245, v65, s[34:35] offset:1088
	global_store_dword v245, v66, s[34:35] offset:2112
	global_store_dword v245, v67, s[34:35] offset:3136
	global_store_dword v244, v68, s[34:35] offset:0
	global_store_dword v244, v69, s[34:35] offset:1024
	global_store_dword v244, v70, s[34:35] offset:2048
	global_store_dword v244, v71, s[34:35] offset:3072
	global_store_dword v244, v72, s[34:35] offset:64
	global_store_dword v244, v73, s[34:35] offset:1088
	global_store_dword v244, v74, s[34:35] offset:2112
	global_store_dword v244, v75, s[34:35] offset:3136
	global_store_dword v243, v76, s[34:35] offset:0
	global_store_dword v243, v77, s[34:35] offset:1024
	global_store_dword v243, v78, s[34:35] offset:2048
	global_store_dword v243, v79, s[34:35] offset:3072
	global_store_dword v243, v80, s[34:35] offset:64
	global_store_dword v243, v81, s[34:35] offset:1088
	global_store_dword v243, v82, s[34:35] offset:2112
	global_store_dword v243, v83, s[34:35] offset:3136
	global_store_dword v242, v84, s[34:35] offset:0
	global_store_dword v242, v85, s[34:35] offset:1024
	global_store_dword v242, v86, s[34:35] offset:2048
	global_store_dword v242, v87, s[34:35] offset:3072
	global_store_dword v242, v88, s[34:35] offset:64
	global_store_dword v242, v89, s[34:35] offset:1088
	global_store_dword v242, v90, s[34:35] offset:2112
	global_store_dword v242, v91, s[34:35] offset:3136
	s_waitcnt vmcnt(0) lgkmcnt(0)
	s_barrier
	s_add_i32 s3, s3, s42
	s_cmpk_lt_i32 s3, 0x100
	s_cbranch_scc1 .Lp3S_item
	s_branch .Lp3_done

; #define LAS __attribute__((address_space(3)))
; __device__ __forceinline__ void gla_scan_item(const Ctx& C, int item, LAS unsigned char* lds, int tid) {
;     const int jx = item >> 3, bh = (item & 7) * 4 + (jx >> 3), sl = jx & 7, b = bh >> 2, h = bh & 3;
;     LAS bf16* Aq = (LAS bf16*)lds;
;     LAS bf16* Bc = (LAS bf16*)(lds + 25600);
;     LAS bf16* Kt = (LAS bf16*)(lds + 38400);
;     const int wave = tid >> 6, lane = tid & 63, l15 = lane & 15, quad = lane >> 4;
;     f32x4 S[2] = {(f32x4){0.f, 0.f, 0.f, 0.f}, (f32x4){0.f, 0.f, 0.f, 0.f}};
;     *(LAS u32x4*)(Bc + (tid >> 4) * 200 + (tid & 15) * 8) = (u32x4){0u, 0u, 0u, 0u};
;     u32x4 rq0A, rq1A, rsA, rk0A, rk1A, rvA = (u32x4){0u, 0u, 0u, 0u}; f32x4 rdA;
;     u32x4 rq0B, rq1B, rsB, rk0B, rk1B, rvB = (u32x4){0u, 0u, 0u, 0u}; f32x4 rdB;
.Lp3V_item:
	s_lshr_b32 s4, s3, 3
	s_and_b32 s41, s4, 7
	s_lshr_b32 s5, s4, 3
	s_and_b32 s37, s3, 7
	s_lshl_b32 s37, s37, 2
	s_add_i32 s37, s37, s5
	s_lshr_b32 s39, s37, 2
	s_and_b32 s40, s37, 3
	s_add_u32 s8, s94, 0x1d800000
	s_addc_u32 s9, s95, 0
	s_lshl_b32 s31, s39, 21
	s_add_u32 s8, s8, s31
	s_addc_u32 s9, s9, 0
	s_lshl_b32 s31, s40, 8
	s_add_u32 s8, s8, s31
	s_addc_u32 s9, s9, 0
	s_add_u32 s10, s94, 0x2f00000
	s_addc_u32 s11, s95, 0
	s_lshl_b32 s31, s37, 18
	s_add_u32 s10, s10, s31
	s_addc_u32 s11, s11, 0
	s_add_u32 s12, s94, 0x3700000
	s_addc_u32 s13, s95, 0
	s_lshl_b32 s31, s37, 19
	s_add_u32 s12, s12, s31
	s_addc_u32 s13, s13, 0
	s_add_u32 s14, s94, 0xd402000
	s_addc_u32 s15, s95, 0
	s_lshl_b32 s31, s39, 25
	s_add_u32 s14, s14, s31
	s_addc_u32 s15, s15, 0
	s_lshl_b32 s31, s40, 9
	s_add_u32 s14, s14, s31
	s_addc_u32 s15, s15, 0
	s_lshl_b32 s31, s41, 6
	s_add_u32 s14, s14, s31
	s_addc_u32 s15, s15, 0
	ds_write_b128 v246, v[8:11]
	s_mov_b32 m0, s46
	s_nop 0
	global_load_lds_dwordx4 v255, s[8:9]
	s_add_i32 m0, s46, 0x400
	s_nop 0
	global_load_lds_dwordx4 v254, s[8:9]
	s_mov_b32 m0, s47
	s_nop 0
	global_load_lds_dwordx4 v253, s[10:11]
	s_mov_b32 m0, s48
	s_nop 0
	global_load_lds_dwordx4 v252, s[12:13]
	s_add_i32 m0, s48, 0x400
	s_nop 0
	global_load_lds_dwordx4 v251, s[12:13]
	s_add_u32 s8, s8, 0x10000
	s_addc_u32 s9, s9, 0
	s_add_u32 s10, s10, 0x2000
	s_addc_u32 s11, s11, 0
	s_add_u32 s12, s12, 0x4000
	s_addc_u32 s13, s13, 0
	s_add_i32 m0, s46, 0xa000
	s_nop 0
	global_load_lds_dwordx4 v255, s[8:9]
	s_add_i32 m0, s46, 0xa400
	s_nop 0
	global_load_lds_dwordx4 v254, s[8:9]
	s_add_i32 m0, s47, 0xa000
	s_nop 0
	global_load_lds_dwordx4 v253, s[10:11]
	s_add_i32 m0, s48, 0xa000
	s_nop 0
	global_load_lds_dwordx4 v252, s[12:13]
	s_add_i32 m0, s48, 0xa400
	s_nop 0
	global_load_lds_dwordx4 v251, s[12:13]
	s_add_u32 s8, s8, 0x10000
	s_addc_u32 s9, s9, 0
	s_add_u32 s10, s10, 0x2000
	s_addc_u32 s11, s11, 0
	s_add_u32 s12, s12, 0x4000
	s_addc_u32 s13, s13, 0
	global_load_dwordx4 v[12:15], v250, s[14:15]
	s_add_u32 s14, s14, 0x100000
	s_addc_u32 s15, s15, 0
	global_load_dwordx4 v[16:19], v250, s[14:15]
	s_add_u32 s14, s14, 0x100000
	s_addc_u32 s15, s15, 0
	global_load_dwordx4 v[20:23], v250, s[14:15]
	s_add_u32 s14, s14, 0x100000
	s_addc_u32 s15, s15, 0
	s_waitcnt vmcnt(0)
	ds_write_b16 v211, v12 offset:0
	ds_write_b16_d16_hi v210, v12 offset:0
	ds_write_b16 v209, v13 offset:0
	ds_write_b16_d16_hi v208, v13 offset:0
	ds_write_b16 v207, v14 offset:0
	ds_write_b16_d16_hi v206, v14 offset:0
	ds_write_b16 v205, v15 offset:0
	ds_write_b16_d16_hi v204, v15 offset:0
	s_mov_b32 s33, 0
	s_waitcnt lgkmcnt(0)
	s_barrier
.Lp3V_loop:
	s_waitcnt vmcnt(6)
	ds_write_b16 v211, v16 offset:12288
	ds_write_b16_d16_hi v210, v16 offset:12288
	ds_write_b16 v209, v17 offset:12288
	ds_write_b16_d16_hi v208, v17 offset:12288
	ds_write_b16 v207, v18 offset:12288
	ds_write_b16_d16_hi v206, v18 offset:12288
	ds_write_b16 v205, v19 offset:12288
	ds_write_b16_d16_hi v204, v19 offset:12288
	s_add_i32 m0, s46, 0x14000
	s_nop 0
	global_load_lds_dwordx4 v255, s[8:9]
	s_add_i32 m0, s46, 0x14400
	s_nop 0
	global_load_lds_dwordx4 v254, s[8:9]
	s_add_i32 m0, s47, 0x14000
	s_nop 0
	global_load_lds_dwordx4 v253, s[10:11]
	s_add_i32 m0, s48, 0x14000
	s_nop 0
	global_load_lds_dwordx4 v252, s[12:13]
	s_add_i32 m0, s48, 0x14400
	s_nop 0
	global_load_lds_dwordx4 v251, s[12:13]
	s_cmp_lt_u32 s33, 29
	s_cselect_b32 s43, 0x10000, 0
	s_add_u32 s8, s8, s43
	s_addc_u32 s9, s9, 0
	s_cmp_lt_u32 s33, 29
	s_cselect_b32 s43, 0x2000, 0
	s_add_u32 s10, s10, s43
	s_addc_u32 s11, s11, 0
	s_cmp_lt_u32 s33, 29
	s_cselect_b32 s43, 0x4000, 0
	s_add_u32 s12, s12, s43
	s_addc_u32 s13, s13, 0
	global_load_dwordx4 v[12:15], v250, s[14:15]
	s_cmp_lt_u32 s33, 28
	s_cselect_b32 s43, 0x100000, 0
	s_add_u32 s14, s14, s43
	s_addc_u32 s15, s15, 0
	s_add_i32 s33, s33, 1
	s_waitcnt vmcnt(7)
	s_waitcnt lgkmcnt(0)
	s_barrier
	s_waitcnt vmcnt(6)
	ds_write_b16 v211, v20 offset:0
	ds_write_b16_d16_hi v210, v20 offset:0
	ds_write_b16 v209, v21 offset:0
	ds_write_b16_d16_hi v208, v21 offset:0
	ds_write_b16 v207, v22 offset:0
	ds_write_b16_d16_hi v206, v22 offset:0
	ds_write_b16 v205, v23 offset:0
	ds_write_b16_d16_hi v204, v23 offset:0
	s_mov_b32 m0, s46
	s_nop 0
	global_load_lds_dwordx4 v255, s[8:9]
	s_add_i32 m0, s46, 0x400
	s_nop 0
	global_load_lds_dwordx4 v254, s[8:9]
	s_mov_b32 m0, s47
	s_nop 0
	global_load_lds_dwordx4 v253, s[10:11]
	s_mov_b32 m0, s48
	s_nop 0
	global_load_lds_dwordx4 v252, s[12:13]
	s_add_i32 m0, s48, 0x400
	s_nop 0
	global_load_lds_dwordx4 v251, s[12:13]
	s_cmp_lt_u32 s33, 29
	s_cselect_b32 s43, 0x10000, 0
	s_add_u32 s8, s8, s43
	s_addc_u32 s9, s9, 0
	s_cmp_lt_u32 s33, 29
	s_cselect_b32 s43, 0x2000, 0
	s_add_u32 s10, s10, s43
	s_addc_u32 s11, s11, 0
	s_cmp_lt_u32 s33, 29
	s_cselect_b32 s43, 0x4000, 0
	s_add_u32 s12, s12, s43
	s_addc_u32 s13, s13, 0
	global_load_dwordx4 v[16:19], v250, s[14:15]
	s_cmp_lt_u32 s33, 28
	s_cselect_b32 s43, 0x100000, 0
	s_add_u32 s14, s14, s43
	s_addc_u32 s15, s15, 0
	s_add_i32 s33, s33, 1
	s_waitcnt vmcnt(7)
	s_waitcnt lgkmcnt(0)
	s_barrier
	s_waitcnt vmcnt(6)
	ds_write_b16 v211, v12 offset:12288
	ds_write_b16_d16_hi v210, v12 offset:12288
	ds_write_b16 v209, v13 offset:12288
	ds_write_b16_d16_hi v208, v13 offset:12288
	ds_write_b16 v207, v14 offset:12288
	ds_write_b16_d16_hi v206, v14 offset:12288
	ds_write_b16 v205, v15 offset:12288
	ds_write_b16_d16_hi v204, v15 offset:12288
	s_add_i32 m0, s46, 0xa000
	s_nop 0
	global_load_lds_dwordx4 v255, s[8:9]
	s_add_i32 m0, s46, 0xa400
	s_nop 0
	global_load_lds_dwordx4 v254, s[8:9]
	s_add_i32 m0, s47, 0xa000
	s_nop 0
	global_load_lds_dwordx4 v253, s[10:11]
	s_add_i32 m0, s48, 0xa000
	s_nop 0
	global_load_lds_dwordx4 v252, s[12:13]
	s_add_i32 m0, s48, 0xa400
	s_nop 0
	global_load_lds_dwordx4 v251, s[12:13]
	s_cmp_lt_u32 s33, 29
	s_cselect_b32 s43, 0x10000, 0
	s_add_u32 s8, s8, s43
	s_addc_u32 s9, s9, 0
	s_cmp_lt_u32 s33, 29
	s_cselect_b32 s43, 0x2000, 0
	s_add_u32 s10, s10, s43
	s_addc_u32 s11, s11, 0
	s_cmp_lt_u32 s33, 29
	s_cselect_b32 s43, 0x4000, 0
	s_add_u32 s12, s12, s43
	s_addc_u32 s13, s13, 0
	global_load_dwordx4 v[20:23], v250, s[14:15]
	s_cmp_lt_u32 s33, 28
	s_cselect_b32 s43, 0x100000, 0
	s_add_u32 s14, s14, s43
	s_addc_u32 s15, s15, 0
	s_add_i32 s33, s33, 1
	s_waitcnt vmcnt(7)
	s_waitcnt lgkmcnt(0)
	s_barrier
	s_waitcnt vmcnt(6)
	ds_write_b16 v211, v16 offset:0
	ds_write_b16_d16_hi v210, v16 offset:0
	ds_write_b16 v209, v17 offset:0
	ds_write_b16_d16_hi v208, v17 offset:0
	ds_write_b16 v207, v18 offset:0
	ds_write_b16_d16_hi v206, v18 offset:0
	ds_write_b16 v205, v19 offset:0
	ds_write_b16_d16_hi v204, v19 offset:0
	s_add_i32 m0, s46, 0x14000
	s_nop 0
	global_load_lds_dwordx4 v255, s[8:9]
	s_add_i32 m0, s46, 0x14400
	s_nop 0
	global_load_lds_dwordx4 v254, s[8:9]
	s_add_i32 m0, s47, 0x14000
	s_nop 0
	global_load_lds_dwordx4 v253, s[10:11]
	s_add_i32 m0, s48, 0x14000
	s_nop 0
	global_load_lds_dwordx4 v252, s[12:13]
	s_add_i32 m0, s48, 0x14400
	s_nop 0
	global_load_lds_dwordx4 v251, s[12:13]
	s_cmp_lt_u32 s33, 29
	s_cselect_b32 s43, 0x10000, 0
	s_add_u32 s8, s8, s43
	s_addc_u32 s9, s9, 0
	s_cmp_lt_u32 s33, 29
	s_cselect_b32 s43, 0x2000, 0
	s_add_u32 s10, s10, s43
	s_addc_u32 s11, s11, 0
	s_cmp_lt_u32 s33, 29
	s_cselect_b32 s43, 0x4000, 0
	s_add_u32 s12, s12, s43
	s_addc_u32 s13, s13, 0
	global_load_dwordx4 v[12:15], v250, s[14:15]
	s_cmp_lt_u32 s33, 28
	s_cselect_b32 s43, 0x100000, 0
	s_add_u32 s14, s14, s43
	s_addc_u32 s15, s15, 0
	s_add_i32 s33, s33, 1
	s_waitcnt vmcnt(7)
	s_waitcnt lgkmcnt(0)
	s_barrier
	s_waitcnt vmcnt(6)
	ds_write_b16 v211, v20 offset:12288
	ds_write_b16_d16_hi v210, v20 offset:12288
	ds_write_b16 v209, v21 offset:12288
	ds_write_b16_d16_hi v208, v21 offset:12288
	ds_write_b16 v207, v22 offset:12288
	ds_write_b16_d16_hi v206, v22 offset:12288
	ds_write_b16 v205, v23 offset:12288
	ds_write_b16_d16_hi v204, v23 offset:12288
	s_mov_b32 m0, s46
	s_nop 0
	global_load_lds_dwordx4 v255, s[8:9]
	s_add_i32 m0, s46, 0x400
	s_nop 0
	global_load_lds_dwordx4 v254, s[8:9]
	s_mov_b32 m0, s47
	s_nop 0
	global_load_lds_dwordx4 v253, s[10:11]
	s_mov_b32 m0, s48
	s_nop 0
	global_load_lds_dwordx4 v252, s[12:13]
	s_add_i32 m0, s48, 0x400
	s_nop 0
	global_load_lds_dwordx4 v251, s[12:13]
	s_cmp_lt_u32 s33, 29
	s_cselect_b32 s43, 0x10000, 0
	s_add_u32 s8, s8, s43
	s_addc_u32 s9, s9, 0
	s_cmp_lt_u32 s33, 29
	s_cselect_b32 s43, 0x2000, 0
	s_add_u32 s10, s10, s43
	s_addc_u32 s11, s11, 0
	s_cmp_lt_u32 s33, 29
	s_cselect_b32 s43, 0x4000, 0
	s_add_u32 s12, s12, s43
	s_addc_u32 s13, s13, 0
	global_load_dwordx4 v[16:19], v250, s[14:15]
	s_cmp_lt_u32 s33, 28
	s_cselect_b32 s43, 0x100000, 0
	s_add_u32 s14, s14, s43
	s_addc_u32 s15, s15, 0
	s_add_i32 s33, s33, 1
	s_waitcnt vmcnt(7)
	s_waitcnt lgkmcnt(0)
	s_barrier
	s_waitcnt vmcnt(6)
	ds_write_b16 v211, v12 offset:0
	ds_write_b16_d16_hi v210, v12 offset:0
	ds_write_b16 v209, v13 offset:0
	ds_write_b16_d16_hi v208, v13 offset:0
	ds_write_b16 v207, v14 offset:0
	ds_write_b16_d16_hi v206, v14 offset:0
	ds_write_b16 v205, v15 offset:0
	ds_write_b16_d16_hi v204, v15 offset:0
	s_add_i32 m0, s46, 0xa000
	s_nop 0
	global_load_lds_dwordx4 v255, s[8:9]
	s_add_i32 m0, s46, 0xa400
	s_nop 0
	global_load_lds_dwordx4 v254, s[8:9]
	s_add_i32 m0, s47, 0xa000
	s_nop 0
	global_load_lds_dwordx4 v253, s[10:11]
	s_add_i32 m0, s48, 0xa000
	s_nop 0
	global_load_lds_dwordx4 v252, s[12:13]
	s_add_i32 m0, s48, 0xa400
	s_nop 0
	global_load_lds_dwordx4 v251, s[12:13]
	s_cmp_lt_u32 s33, 29
	s_cselect_b32 s43, 0x10000, 0
	s_add_u32 s8, s8, s43
	s_addc_u32 s9, s9, 0
	s_cmp_lt_u32 s33, 29
	s_cselect_b32 s43, 0x2000, 0
	s_add_u32 s10, s10, s43
	s_addc_u32 s11, s11, 0
	s_cmp_lt_u32 s33, 29
	s_cselect_b32 s43, 0x4000, 0
	s_add_u32 s12, s12, s43
	s_addc_u32 s13, s13, 0
	global_load_dwordx4 v[20:23], v250, s[14:15]
	s_cmp_lt_u32 s33, 28
	s_cselect_b32 s43, 0x100000, 0
	s_add_u32 s14, s14, s43
	s_addc_u32 s15, s15, 0
	s_add_i32 s33, s33, 1
	s_waitcnt vmcnt(7)
	s_waitcnt lgkmcnt(0)
	s_barrier
	s_cmp_lt_u32 s33, 30
	s_cbranch_scc1 .Lp3V_loop
	s_waitcnt vmcnt(6)
	ds_write_b16 v211, v16 offset:12288
	ds_write_b16_d16_hi v210, v16 offset:12288
	ds_write_b16 v209, v17 offset:12288
	ds_write_b16_d16_hi v208, v17 offset:12288
	ds_write_b16 v207, v18 offset:12288
	ds_write_b16_d16_hi v206, v18 offset:12288
	ds_write_b16 v205, v19 offset:12288
	ds_write_b16_d16_hi v204, v19 offset:12288
	s_add_i32 m0, s46, 0x14000
	s_nop 0
	global_load_lds_dwordx4 v255, s[8:9]
	s_add_i32 m0, s46, 0x14400
	s_nop 0
	global_load_lds_dwordx4 v254, s[8:9]
	s_add_i32 m0, s47, 0x14000
	s_nop 0
	global_load_lds_dwordx4 v253, s[10:11]
	s_add_i32 m0, s48, 0x14000
	s_nop 0
	global_load_lds_dwordx4 v252, s[12:13]
	s_add_i32 m0, s48, 0x14400
	s_nop 0
	global_load_lds_dwordx4 v251, s[12:13]
	s_cmp_lt_u32 s33, 29
	s_cselect_b32 s43, 0x10000, 0
	s_add_u32 s8, s8, s43
	s_addc_u32 s9, s9, 0
	s_cmp_lt_u32 s33, 29
	s_cselect_b32 s43, 0x2000, 0
	s_add_u32 s10, s10, s43
	s_addc_u32 s11, s11, 0
	s_cmp_lt_u32 s33, 29
	s_cselect_b32 s43, 0x4000, 0
	s_add_u32 s12, s12, s43
	s_addc_u32 s13, s13, 0
	global_load_dwordx4 v[12:15], v250, s[14:15]
	s_cmp_lt_u32 s33, 28
	s_cselect_b32 s43, 0x100000, 0
	s_add_u32 s14, s14, s43
	s_addc_u32 s15, s15, 0
	s_add_i32 s33, s33, 1
	s_waitcnt vmcnt(7)
	s_waitcnt lgkmcnt(0)
	s_barrier
	s_waitcnt vmcnt(6)
	ds_write_b16 v211, v20 offset:0
	ds_write_b16_d16_hi v210, v20 offset:0
	ds_write_b16 v209, v21 offset:0
	ds_write_b16_d16_hi v208, v21 offset:0
	ds_write_b16 v207, v22 offset:0
	ds_write_b16_d16_hi v206, v22 offset:0
	ds_write_b16 v205, v23 offset:0
	ds_write_b16_d16_hi v204, v23 offset:0
	s_mov_b32 m0, s46
	s_nop 0
	global_load_lds_dwordx4 v255, s[8:9]
	s_add_i32 m0, s46, 0x400
	s_nop 0
	global_load_lds_dwordx4 v254, s[8:9]
	s_mov_b32 m0, s47
	s_nop 0
	global_load_lds_dwordx4 v253, s[10:11]
	s_mov_b32 m0, s48
	s_nop 0
	global_load_lds_dwordx4 v252, s[12:13]
	s_add_i32 m0, s48, 0x400
	s_nop 0
	global_load_lds_dwordx4 v251, s[12:13]
	s_cmp_lt_u32 s33, 29
	s_cselect_b32 s43, 0x10000, 0
	s_add_u32 s8, s8, s43
	s_addc_u32 s9, s9, 0
	s_cmp_lt_u32 s33, 29
	s_cselect_b32 s43, 0x2000, 0
	s_add_u32 s10, s10, s43
	s_addc_u32 s11, s11, 0
	s_cmp_lt_u32 s33, 29
	s_cselect_b32 s43, 0x4000, 0
	s_add_u32 s12, s12, s43
	s_addc_u32 s13, s13, 0
	global_load_dwordx4 v[16:19], v250, s[14:15]
	s_cmp_lt_u32 s33, 28
	s_cselect_b32 s43, 0x100000, 0
	s_add_u32 s14, s14, s43
	s_addc_u32 s15, s15, 0
	s_add_i32 s33, s33, 1
	s_waitcnt vmcnt(7)
	s_waitcnt lgkmcnt(0)
	s_barrier
	s_waitcnt vmcnt(0) lgkmcnt(0)
	s_barrier
	s_add_i32 s3, s3, s42
	s_cmpk_lt_i32 s3, 0x100
	s_cbranch_scc1 .Lp3V_item
	s_branch .Lp3_done
